# attention MODE0 loop hand-rescheduled: QK as two back-to-back accumulation chains with deep K prefetch, V ring prefetch with counted waits, softmax VALU spread over MFMA gaps, waves 4-7 staggered, sli
# speedup vs baseline: 1.0108x; 1.0069x over previous
; #define SBAR() __builtin_amdgcn_sched_barrier(0)
; #define QKT(P0, P1, KS) do { if (MODE == 1) qkt_lds(P0, P1, KS, qs, r32, hi); else qkt(P0, P1, KS, qr, r32, hi); } while (0)
; __device__ __forceinline__ void finishSM(f32x16& p0, f32x16& p1, float alpha, float& l_reg, bf16x8& pa0, bf16x8& pa1, bf16x8& pa2, bf16x8& pa3) {
;   for (int r = 0; r < 16; ++r) p1[r] = __builtin_amdgcn_exp2f(p1[r]);
;   float ps = 0; for (int r = 0; r < 16; ++r) ps += p0[r]; for (int r = 0; r < 16; ++r) ps += p1[r];
;   { auto rr = __builtin_amdgcn_permlane32_swap(__float_as_uint(ps), __float_as_uint(ps), false, false);
;     ps = __uint_as_float(rr[0]) + __uint_as_float(rr[1]); }
;   l_reg = l_reg * alpha + ps;
;     ...
;   PK4(p0, 0, pa0); PK4(p0, 8, pa1); PK4(p1, 0, pa2); PK4(p1, 8, pa3);
;     ...
; }
; __device__ __forceinline__ void qkt(f32x16& p0, f32x16& p1, const u16* Ks, const bf16x8* qr, int r32, int hi) {
;   p0 = f32x16{}; p1 = f32x16{};
;   for (int d0 = 0; d0 < 8; ++d0) { int cb = (d0 * 16 + hi * 8) * 2;
;     bf16x8 b0 = *reinterpret_cast<const bf16x8*>((const char*)Ks + KSWZ(r32, cb));
;     bf16x8 b1 = *reinterpret_cast<const bf16x8*>((const char*)Ks + KSWZ(32 + r32, cb));
;     p0 = __builtin_amdgcn_mfma_f32_32x32x16_bf16(b0, qr[d0], p0, 0, 0, 0);
;     p1 = __builtin_amdgcn_mfma_f32_32x32x16_bf16(b1, qr[d0], p1, 0, 0, 0); }
; }
; template <int MODE> ...
;     ...
;     for (int j = 1; j + 1 < NT; j += 2) {
;       const int s0_ = sj, s1_ = sj == 2 ? 0 : sj + 1, s2_ = s1_ == 2 ? 0 : s1_ + 1;
;       SBAR(); QKT(pB0, pB1, (u16*)((char*)K_lds + s0_ * SHM_K));
;       finishSM(pA0, pA1, alA, l_reg, pa0, pa1, pa2, pa3); SBAR();
;       { const int tn = (j + 2 < NT) ? j + 2 : NT - 1; SLOAD(SO, tn); } SBAR();
;       pv_d0(o, vb0 + s2_ * (int)SHM_V, pa0, pa1, pa2, pa3); partialSM(pB0, pB1, m_reg, mnB, alB);
.LBB0_474:
	s_add_i32 s7, s89, 1
	s_cmp_lg_u32 s89, 2
	s_cselect_b32 s66, s7, 0
	s_add_i32 s7, s66, 1
	s_cmp_lg_u32 s66, 2
	s_mov_b32 s6, s89
	s_cselect_b32 s89, s7, 0
	s_lshl_b32 s93, s6, 14
	s_add_i32 s6, s93, 0
	v_add_u32_e32 v254, s6, v189
	ds_read_b128 v[68:71], v254 offset:49152
	ds_read_b128 v[72:75], v254 offset:49280
	v_add_u32_e32 v254, s6, v190
	ds_read_b128 v[76:79], v254 offset:49152
	ds_read_b128 v[80:83], v254 offset:49280
	v_add_u32_e32 v254, s6, v191
	ds_read_b128 v[220:223], v254 offset:49152
	ds_read_b128 v[224:227], v254 offset:49280
	v_add_u32_e32 v254, s6, v192
	ds_read_b128 v[228:231], v254 offset:49152
	ds_read_b128 v[232:235], v254 offset:49280
	v_add_u32_e32 v254, s6, v189
	ds_read_b128 v[236:239], v254 offset:57344
	ds_read_b128 v[240:243], v254 offset:57472
	v_exp_f32_e32 v160, v160
	v_exp_f32_e32 v161, v161
	v_exp_f32_e32 v158, v158
	v_exp_f32_e32 v159, v159
	v_exp_f32_e32 v156, v156
	v_exp_f32_e32 v157, v157
	v_exp_f32_e32 v154, v154
	v_exp_f32_e32 v155, v155
	v_exp_f32_e32 v152, v152
	v_exp_f32_e32 v153, v153
	v_exp_f32_e32 v150, v150
	v_exp_f32_e32 v151, v151
	s_waitcnt lgkmcnt(9)
	v_mfma_f32_32x32x16_bf16 v[84:99], v[68:71], v[100:103], 0
	v_exp_f32_e32 v148, v148
	v_exp_f32_e32 v149, v149
	v_exp_f32_e32 v2, v162
	v_exp_f32_e32 v162, v163
	v_add_f32_e32 v163, 0, v216
	s_waitcnt lgkmcnt(8)
	v_mfma_f32_32x32x16_bf16 v[84:99], v[72:75], v[116:119], v[84:99]
	v_add_f32_e32 v163, v218, v163
	v_add_f32_e32 v163, v214, v163
	v_add_f32_e32 v163, v217, v163
	v_add_f32_e32 v163, v213, v163
	v_add_f32_e32 v163, v215, v163
	s_waitcnt lgkmcnt(7)
	v_mfma_f32_32x32x16_bf16 v[84:99], v[76:79], v[104:107], v[84:99]
	v_add_f32_e32 v163, v211, v163
	v_add_f32_e32 v163, v212, v163
	v_add_f32_e32 v163, v208, v163
	v_add_f32_e32 v163, v210, v163
	v_add_f32_e32 v163, v207, v163
	s_waitcnt lgkmcnt(6)
	v_mfma_f32_32x32x16_bf16 v[84:99], v[80:83], v[120:123], v[84:99]
	v_add_f32_e32 v163, v209, v163
	v_add_f32_e32 v163, v204, v163
	v_add_f32_e32 v163, v206, v163
	v_add_f32_e32 v163, v203, v163
	v_add_f32_e32 v163, v205, v163
	s_waitcnt lgkmcnt(5)
	v_mfma_f32_32x32x16_bf16 v[84:99], v[220:223], v[108:111], v[84:99]
	v_add_u32_e32 v254, s6, v190
	ds_read_b128 v[220:223], v254 offset:57344
	v_add_f32_e32 v163, v2, v163
	v_add_f32_e32 v163, v162, v163
	v_add_f32_e32 v163, v160, v163
	v_add_f32_e32 v163, v161, v163
	v_add_f32_e32 v163, v158, v163
	s_waitcnt lgkmcnt(5)
	v_mfma_f32_32x32x16_bf16 v[84:99], v[224:227], v[124:127], v[84:99]
	ds_read_b128 v[224:227], v254 offset:57472
	v_add_f32_e32 v163, v159, v163
	v_add_f32_e32 v163, v156, v163
	v_add_f32_e32 v163, v157, v163
	v_add_f32_e32 v163, v154, v163
	v_add_f32_e32 v163, v155, v163
	s_waitcnt lgkmcnt(5)
	v_mfma_f32_32x32x16_bf16 v[84:99], v[228:231], v[112:115], v[84:99]
	v_add_u32_e32 v254, s6, v191
	ds_read_b128 v[228:231], v254 offset:57344
	v_add_f32_e32 v163, v152, v163
	v_add_f32_e32 v163, v153, v163
	v_add_f32_e32 v163, v150, v163
	v_add_f32_e32 v163, v151, v163
	s_waitcnt lgkmcnt(5)
	v_mfma_f32_32x32x16_bf16 v[84:99], v[232:235], v[128:131], v[84:99]
	ds_read_b128 v[232:235], v254 offset:57472
	v_add_f32_e32 v163, v148, v163
	v_add_f32_e32 v200, v149, v163
	v_mov_b32_e32 v201, v200
	v_cvt_pk_bf16_f32 v216, v216, v218
	s_waitcnt lgkmcnt(5)
	v_mfma_f32_32x32x16_bf16 v[68:83], v[236:239], v[100:103], 0
	v_add_u32_e32 v254, s6, v192
	ds_read_b128 v[236:239], v254 offset:57344
	v_cvt_pk_bf16_f32 v217, v214, v217
	v_cvt_pk_bf16_f32 v218, v213, v215
	v_cvt_pk_bf16_f32 v219, v211, v212
	v_cvt_pk_bf16_f32 v208, v208, v210
	s_waitcnt lgkmcnt(5)
	v_mfma_f32_32x32x16_bf16 v[68:83], v[240:243], v[116:119], v[68:83]
	ds_read_b128 v[240:243], v254 offset:57472
	v_cvt_pk_bf16_f32 v209, v207, v209
	v_cvt_pk_bf16_f32 v210, v204, v206
	v_cvt_pk_bf16_f32 v211, v203, v205
	v_cvt_pk_bf16_f32 v202, v2, v162
	s_waitcnt lgkmcnt(5)
	v_mfma_f32_32x32x16_bf16 v[68:83], v[220:223], v[104:107], v[68:83]
	v_cvt_pk_bf16_f32 v203, v160, v161
	v_cvt_pk_bf16_f32 v204, v158, v159
	v_permlane32_swap_b32_e32 v200, v201
	v_cvt_pk_bf16_f32 v205, v156, v157
	s_waitcnt lgkmcnt(4)
	v_mfma_f32_32x32x16_bf16 v[68:83], v[224:227], v[120:123], v[68:83]
	v_permlane32_swap_b32_e32 v202, v204
	v_cvt_pk_bf16_f32 v212, v154, v155
	v_cvt_pk_bf16_f32 v213, v152, v153
	v_cvt_pk_bf16_f32 v214, v150, v151
	s_waitcnt lgkmcnt(3)
	v_mfma_f32_32x32x16_bf16 v[68:83], v[228:231], v[108:111], v[68:83]
	v_cvt_pk_bf16_f32 v215, v148, v149
	v_permlane32_swap_b32_e32 v216, v218
	v_permlane32_swap_b32_e32 v217, v219
	v_permlane32_swap_b32_e32 v208, v210
	s_waitcnt lgkmcnt(2)
	v_mfma_f32_32x32x16_bf16 v[68:83], v[232:235], v[124:127], v[68:83]
	v_permlane32_swap_b32_e32 v209, v211
	v_permlane32_swap_b32_e32 v203, v205
	v_permlane32_swap_b32_e32 v212, v214
	v_permlane32_swap_b32_e32 v213, v215
	s_waitcnt lgkmcnt(1)
	v_mfma_f32_32x32x16_bf16 v[68:83], v[236:239], v[112:115], v[68:83]
	s_add_i32 s91, s16, -1
	s_min_u32 s7, s91, s90
	s_add_i32 s7, s7, s88
	s_lshl_b32 s7, s7, 6
	s_waitcnt lgkmcnt(0)
	v_mfma_f32_32x32x16_bf16 v[68:83], v[240:243], v[128:131], v[68:83]
	v_add_u32_e32 v244, s7, v167
	v_add_u32_e32 v245, s7, v185
	v_lshl_or_b32 v244, v244, 8, v182
	v_lshl_or_b32 v245, v245, 8, v182
	global_load_dwordx4 v[152:155], v244, s[58:59]
	global_load_dwordx4 v[148:151], v245, s[58:59]
	global_load_dwordx4 v[160:163], v244, s[64:65]
	global_load_dwordx4 v[156:159], v245, s[64:65]
	s_lshl_b32 s94, s89, 14
	v_add_u32_e32 v254, s94, v197
	ds_read_b64_tr_b16 v[220:221], v254 offset:0
	ds_read_b64_tr_b16 v[222:223], v254 offset:2048
	ds_read_b64_tr_b16 v[224:225], v254 offset:4096
	ds_read_b64_tr_b16 v[226:227], v254 offset:6144
	ds_read_b64_tr_b16 v[228:229], v254 offset:8192
	ds_read_b64_tr_b16 v[230:231], v254 offset:10240
	ds_read_b64_tr_b16 v[232:233], v254 offset:12288
	ds_read_b64_tr_b16 v[234:235], v254 offset:14336
	ds_read_b64_tr_b16 v[236:237], v254 offset:512
	ds_read_b64_tr_b16 v[238:239], v254 offset:2560
	s_waitcnt lgkmcnt(6)
; #define SBAR() __builtin_amdgcn_sched_barrier(0)
; __device__ __forceinline__ void partialSM(f32x16& p0, f32x16& p1, float& m_reg, float& mn, float& alpha) {
;   constexpr float C = SCALE * 1.4426950408889634f;
;   float pmax = p0[0]; for (int r = 1; r < 16; ++r) pmax = fmaxf(pmax, p0[r]); for (int r = 0; r < 16; ++r) pmax = fmaxf(pmax, p1[r]);
;   { auto rr = __builtin_amdgcn_permlane32_swap(__float_as_uint(pmax), __float_as_uint(pmax), false, false);
;     pmax = fmaxf(__uint_as_float(rr[0]), __uint_as_float(rr[1])); }
;   if (__builtin_expect(__all(pmax - m_reg <= THR / SCALE), 1)) { mn = m_reg; alpha = 1.f; }
;   else { mn = fmaxf(m_reg, pmax); alpha = __builtin_amdgcn_exp2f((m_reg - mn) * C); m_reg = mn; }
; template <int D0> __device__ __forceinline__ void pv_one(f32x16& od, int vb, bf16x8 pa0, bf16x8 pa1, bf16x8 pa2, bf16x8 pa3) {
;   const s16x4 l0 = tr_read<v_rd_off(D0, 0, 0)>(vb), h0 = tr_read<v_rd_off(D0, 0, 1)>(vb), l1 = tr_read<v_rd_off(D0, 1, 0)>(vb), h1 = tr_read<v_rd_off(D0, 1, 1)>(vb);
;   const s16x4 l2 = tr_read<v_rd_off(D0, 2, 0)>(vb), h2 = tr_read<v_rd_off(D0, 2, 1)>(vb), l3 = tr_read<v_rd_off(D0, 3, 0)>(vb), h3 = tr_read<v_rd_off(D0, 3, 1)>(vb);
;   asm volatile("s_waitcnt lgkmcnt(0)" ::: "memory"); SBAR();
;     ...
;   od = __builtin_amdgcn_mfma_f32_32x32x16_bf16(pa0, PK(l0, h0), od, 0, 0, 0);
;   od = __builtin_amdgcn_mfma_f32_32x32x16_bf16(pa1, PK(l1, h1), od, 0, 0, 0);
;   od = __builtin_amdgcn_mfma_f32_32x32x16_bf16(pa2, PK(l2, h2), od, 0, 0, 0);
;   od = __builtin_amdgcn_mfma_f32_32x32x16_bf16(pa3, PK(l3, h3), od, 0, 0, 0);
;     ...
; }
; __device__ __forceinline__ void pv_d0(f32x16* o, int vb, bf16x8 pa0, bf16x8 pa1, bf16x8 pa2, bf16x8 pa3) {
;   pv_one<0>(o[0], vb, pa0, pa1, pa2, pa3); pv_one<1>(o[1], vb, pa0, pa1, pa2, pa3); pv_one<2>(o[2], vb, pa0, pa1, pa2, pa3); pv_one<3>(o[3], vb, pa0, pa1, pa2, pa3);
	v_mfma_f32_32x32x16_bf16 v[52:67], v[216:219], v[220:223], v[52:67]
	ds_read_b64_tr_b16 v[240:241], v254 offset:4608
	ds_read_b64_tr_b16 v[242:243], v254 offset:6656
	v_max_f32_e32 v2, v85, v85
	v_max_f32_e32 v253, v84, v84
	v_mfma_f32_32x32x16_bf16 v[52:67], v[208:211], v[224:227], v[52:67]
	ds_read_b64_tr_b16 v[220:221], v254 offset:8704
	ds_read_b64_tr_b16 v[222:223], v254 offset:10752
	v_max_f32_e32 v2, v253, v2
	v_max3_f32 v2, v2, v86, v87
	s_waitcnt lgkmcnt(6)
	v_mfma_f32_32x32x16_bf16 v[52:67], v[202:205], v[228:231], v[52:67]
	ds_read_b64_tr_b16 v[224:225], v254 offset:12800
	ds_read_b64_tr_b16 v[226:227], v254 offset:14848
	v_max3_f32 v2, v2, v88, v89
	v_max3_f32 v2, v2, v90, v91
	v_mfma_f32_32x32x16_bf16 v[52:67], v[212:215], v[232:235], v[52:67]
	ds_read_b64_tr_b16 v[228:229], v254 offset:1024
	ds_read_b64_tr_b16 v[230:231], v254 offset:3072
	v_max3_f32 v2, v2, v92, v93
	v_max3_f32 v2, v2, v94, v95
	s_waitcnt lgkmcnt(6)
	v_mfma_f32_32x32x16_bf16 v[36:51], v[216:219], v[236:239], v[36:51]
	ds_read_b64_tr_b16 v[232:233], v254 offset:5120
	ds_read_b64_tr_b16 v[234:235], v254 offset:7168
	v_max3_f32 v2, v2, v96, v97
	v_max3_f32 v2, v2, v98, v99
	v_mfma_f32_32x32x16_bf16 v[36:51], v[208:211], v[240:243], v[36:51]
	ds_read_b64_tr_b16 v[236:237], v254 offset:9216
	ds_read_b64_tr_b16 v[238:239], v254 offset:11264
	v_max3_f32 v2, v2, v68, v69
	v_max3_f32 v2, v2, v70, v71
	s_waitcnt lgkmcnt(6)
	v_mfma_f32_32x32x16_bf16 v[36:51], v[202:205], v[220:223], v[36:51]
	ds_read_b64_tr_b16 v[240:241], v254 offset:13312
	ds_read_b64_tr_b16 v[242:243], v254 offset:15360
	v_max3_f32 v2, v2, v72, v73
	v_mfma_f32_32x32x16_bf16 v[36:51], v[212:215], v[224:227], v[36:51]
	ds_read_b64_tr_b16 v[220:221], v254 offset:1536
	ds_read_b64_tr_b16 v[222:223], v254 offset:3584
	v_max3_f32 v2, v2, v74, v75
	s_waitcnt lgkmcnt(6)
	v_mfma_f32_32x32x16_bf16 v[20:35], v[216:219], v[228:231], v[20:35]
	ds_read_b64_tr_b16 v[224:225], v254 offset:5632
	ds_read_b64_tr_b16 v[226:227], v254 offset:7680
	v_max3_f32 v2, v2, v76, v77
	v_mfma_f32_32x32x16_bf16 v[20:35], v[208:211], v[232:235], v[20:35]
	ds_read_b64_tr_b16 v[228:229], v254 offset:9728
	ds_read_b64_tr_b16 v[230:231], v254 offset:11776
	v_max3_f32 v2, v2, v78, v79
	s_waitcnt lgkmcnt(6)
	v_mfma_f32_32x32x16_bf16 v[20:35], v[202:205], v[236:239], v[20:35]
	ds_read_b64_tr_b16 v[232:233], v254 offset:13824
	ds_read_b64_tr_b16 v[234:235], v254 offset:15872
	v_max3_f32 v2, v2, v80, v81
	v_mfma_f32_32x32x16_bf16 v[20:35], v[212:215], v[240:243], v[20:35]
	v_max3_f32 v2, v2, v82, v83
	s_waitcnt lgkmcnt(4)
	v_mfma_f32_32x32x16_bf16 v[4:19], v[216:219], v[220:223], v[4:19]
	s_waitcnt vmcnt(4)
	v_mfma_f32_32x32x16_bf16 v[4:19], v[208:211], v[224:227], v[4:19]
	s_waitcnt lgkmcnt(0)
	v_mfma_f32_32x32x16_bf16 v[4:19], v[202:205], v[228:231], v[4:19]
	v_mov_b32_e32 v253, v2
	s_nop 1
	v_permlane32_swap_b32_e32 v2, v253
	v_max_f32_e32 v253, v253, v253
	v_max_f32_e32 v2, v2, v2
	v_max_f32_e32 v2, v2, v253
	v_sub_f32_e32 v253, v2, v166
	v_cmp_ge_f32_e32 vcc, s74, v253
	v_max_f32_e32 v253, v166, v166
	v_max_f32_e32 v2, v253, v2
	v_mfma_f32_32x32x16_bf16 v[4:19], v[212:215], v[232:235], v[4:19]
	v_sub_f32_e32 v202, v166, v2
	s_cmp_eq_u64 vcc, exec
	v_mul_f32_e32 v202, 0x3e0293ee, v202
	s_cselect_b64 s[6:7], -1, 0
	v_exp_f32_e32 v202, v202
	s_lshl_b32 s92, s66, 14
	s_add_i32 s95, s92, 0
	v_add_u32_e32 v203, s95, v184
	ds_write_b128 v203, v[136:139]
	v_add_u32_e32 v136, s95, v186
	v_cndmask_b32_e64 v202, v202, 1.0, s[6:7]
	ds_write_b128 v136, v[132:135]
	v_add_u32_e32 v132, s95, v187
	ds_write_b128 v132, v[144:147] offset:49152
	v_add_u32_e32 v132, s95, v188
	v_cmp_gt_f32_e32 vcc, 1.0, v202
	s_waitcnt vmcnt(4)
	ds_write_b128 v132, v[140:143] offset:49152
	s_cbranch_vccz .LBB0_478
	s_and_saveexec_b64 s[66:67], s[4:5]
	ds_write_b32 v183, v202 offset:128
	s_or_b64 exec, exec, s[66:67]
	s_waitcnt lgkmcnt(0)
	v_add_u32_e32 v144, v181, v180
	ds_read_b128 v[132:135], v144 offset:224
	ds_read_b128 v[136:139], v144 offset:192
	ds_read_b128 v[140:143], v144 offset:160
	ds_read_b128 v[144:147], v144 offset:128
	s_waitcnt lgkmcnt(3)
	v_pk_mul_f32 v[64:65], v[64:65], v[132:133]
	s_waitcnt lgkmcnt(2)
	v_pk_mul_f32 v[60:61], v[60:61], v[136:137]
	s_waitcnt lgkmcnt(1)
	v_pk_mul_f32 v[56:57], v[56:57], v[140:141]
	v_pk_mul_f32 v[66:67], v[66:67], v[134:135]
	v_pk_mul_f32 v[62:63], v[62:63], v[138:139]
	v_pk_mul_f32 v[58:59], v[58:59], v[142:143]
	s_waitcnt lgkmcnt(0)
	v_pk_mul_f32 v[54:55], v[54:55], v[146:147]
	v_pk_mul_f32 v[52:53], v[52:53], v[144:145]
	v_pk_mul_f32 v[48:49], v[48:49], v[132:133]
	v_pk_mul_f32 v[44:45], v[44:45], v[136:137]
	v_pk_mul_f32 v[40:41], v[40:41], v[140:141]
	v_pk_mul_f32 v[50:51], v[50:51], v[134:135]
	v_pk_mul_f32 v[46:47], v[46:47], v[138:139]
	v_pk_mul_f32 v[42:43], v[42:43], v[142:143]
	v_pk_mul_f32 v[38:39], v[38:39], v[146:147]
	v_pk_mul_f32 v[36:37], v[36:37], v[144:145]
	v_pk_mul_f32 v[32:33], v[32:33], v[132:133]
	v_pk_mul_f32 v[28:29], v[28:29], v[136:137]
	v_pk_mul_f32 v[24:25], v[24:25], v[140:141]
	v_pk_mul_f32 v[34:35], v[34:35], v[134:135]
	v_pk_mul_f32 v[30:31], v[30:31], v[138:139]
	v_pk_mul_f32 v[26:27], v[26:27], v[142:143]
	v_pk_mul_f32 v[22:23], v[22:23], v[146:147]
	v_pk_mul_f32 v[20:21], v[20:21], v[144:145]
	v_pk_mul_f32 v[16:17], v[16:17], v[132:133]
	v_pk_mul_f32 v[12:13], v[12:13], v[136:137]
	v_pk_mul_f32 v[8:9], v[8:9], v[140:141]
	v_pk_mul_f32 v[18:19], v[18:19], v[134:135]
	v_pk_mul_f32 v[14:15], v[14:15], v[138:139]
	v_pk_mul_f32 v[10:11], v[10:11], v[142:143]
	v_pk_mul_f32 v[6:7], v[6:7], v[146:147]
	v_pk_mul_f32 v[4:5], v[4:5], v[144:145]
; __device__ __forceinline__ void partialSM(f32x16& p0, f32x16& p1, float& m_reg, float& mn, float& alpha) {
;   constexpr float C = SCALE * 1.4426950408889634f;
;   float pmax = p0[0]; for (int r = 1; r < 16; ++r) pmax = fmaxf(pmax, p0[r]); for (int r = 0; r < 16; ++r) pmax = fmaxf(pmax, p1[r]);
;   { auto rr = __builtin_amdgcn_permlane32_swap(__float_as_uint(pmax), __float_as_uint(pmax), false, false);
;     pmax = fmaxf(__uint_as_float(rr[0]), __uint_as_float(rr[1])); }
;   if (__builtin_expect(__all(pmax - m_reg <= THR / SCALE), 1)) { mn = m_reg; alpha = 1.f; }
;   else { mn = fmaxf(m_reg, pmax); alpha = __builtin_amdgcn_exp2f((m_reg - mn) * C); m_reg = mn; }
;   float mnC = -mn * C;
;   for (int r = 0; r < 16; ++r) p0[r] = fmaf(p0[r], C, mnC); for (int r = 0; r < 16; ++r) p1[r] = fmaf(p1[r], C, mnC);
;   for (int r = 0; r < 16; ++r) p0[r] = __builtin_amdgcn_exp2f(p0[r]);
; }
; __device__ __forceinline__ void qkt(f32x16& p0, f32x16& p1, const u16* Ks, const bf16x8* qr, int r32, int hi) {
;   p0 = f32x16{}; p1 = f32x16{};
;   for (int d0 = 0; d0 < 8; ++d0) { int cb = (d0 * 16 + hi * 8) * 2;
;     bf16x8 b0 = *reinterpret_cast<const bf16x8*>((const char*)Ks + KSWZ(r32, cb));
;     bf16x8 b1 = *reinterpret_cast<const bf16x8*>((const char*)Ks + KSWZ(32 + r32, cb));
;     p0 = __builtin_amdgcn_mfma_f32_32x32x16_bf16(b0, qr[d0], p0, 0, 0, 0);
;     p1 = __builtin_amdgcn_mfma_f32_32x32x16_bf16(b1, qr[d0], p1, 0, 0, 0); }
; }
.LBB0_478:
	v_cndmask_b32_e64 v2, v2, v166, s[6:7]
	v_mul_f32_e32 v140, 0xbe0293ee, v2
	v_fmamk_f32 v93, v93, 0x3e0293ee, v140
	v_exp_f32_e32 v221, v93
	v_fmamk_f32 v84, v84, 0x3e0293ee, v140
	v_fmamk_f32 v85, v85, 0x3e0293ee, v140
	v_fmamk_f32 v86, v86, 0x3e0293ee, v140
	v_fmamk_f32 v87, v87, 0x3e0293ee, v140
	v_fmamk_f32 v88, v88, 0x3e0293ee, v140
	v_fmamk_f32 v89, v89, 0x3e0293ee, v140
	v_fmamk_f32 v90, v90, 0x3e0293ee, v140
	v_fmamk_f32 v91, v91, 0x3e0293ee, v140
	v_fmamk_f32 v92, v92, 0x3e0293ee, v140
	v_fmamk_f32 v94, v94, 0x3e0293ee, v140
	v_fmamk_f32 v95, v95, 0x3e0293ee, v140
	v_fmamk_f32 v96, v96, 0x3e0293ee, v140
	v_fmamk_f32 v97, v97, 0x3e0293ee, v140
	v_fmamk_f32 v98, v98, 0x3e0293ee, v140
	v_fmamk_f32 v99, v99, 0x3e0293ee, v140
	v_fmamk_f32 v141, v68, 0x3e0293ee, v140
	v_fmamk_f32 v142, v69, 0x3e0293ee, v140
	v_fmamk_f32 v143, v70, 0x3e0293ee, v140
	v_fmamk_f32 v144, v71, 0x3e0293ee, v140
	v_fmamk_f32 v145, v72, 0x3e0293ee, v140
	v_fmamk_f32 v146, v73, 0x3e0293ee, v140
	v_fmamk_f32 v147, v74, 0x3e0293ee, v140
	v_fmamk_f32 v166, v75, 0x3e0293ee, v140
	v_fmamk_f32 v203, v76, 0x3e0293ee, v140
	v_fmamk_f32 v204, v77, 0x3e0293ee, v140
	v_fmamk_f32 v205, v78, 0x3e0293ee, v140
	v_fmamk_f32 v206, v79, 0x3e0293ee, v140
	v_fmamk_f32 v207, v80, 0x3e0293ee, v140
	v_fmamk_f32 v208, v81, 0x3e0293ee, v140
	v_fmamk_f32 v209, v82, 0x3e0293ee, v140
	v_fmac_f32_e32 v140, 0x3e0293ee, v83
	v_exp_f32_e32 v210, v84
	v_exp_f32_e32 v211, v85
	v_exp_f32_e32 v212, v86
	v_exp_f32_e32 v213, v87
	v_exp_f32_e32 v214, v88
	v_exp_f32_e32 v215, v89
	v_exp_f32_e32 v216, v90
	v_exp_f32_e32 v217, v91
	v_exp_f32_e32 v218, v92
	v_exp_f32_e32 v222, v94
	v_exp_f32_e32 v223, v95
	v_exp_f32_e32 v224, v96
	v_exp_f32_e32 v225, v97
	v_exp_f32_e32 v226, v98
	v_exp_f32_e32 v227, v99
	s_waitcnt lgkmcnt(0)
	s_barrier
	v_add_u32_e32 v254, s95, v189
	ds_read_b128 v[68:71], v254 offset:49152
	ds_read_b128 v[72:75], v254 offset:49280
	v_add_u32_e32 v254, s95, v190
	ds_read_b128 v[76:79], v254 offset:49152
	ds_read_b128 v[80:83], v254 offset:49280
	v_add_u32_e32 v254, s95, v191
	ds_read_b128 v[228:231], v254 offset:49152
	ds_read_b128 v[232:235], v254 offset:49280
	v_add_u32_e32 v254, s95, v192
	ds_read_b128 v[236:239], v254 offset:49152
	ds_read_b128 v[240:243], v254 offset:49280
	v_add_u32_e32 v254, s95, v189
	ds_read_b128 v[246:249], v254 offset:57344
	ds_read_b128 v[250:253], v254 offset:57472
	v_exp_f32_e32 v140, v140
	v_exp_f32_e32 v139, v166
	v_add_f32_e32 v166, 0, v210
	v_add_f32_e32 v166, v211, v166
	v_add_f32_e32 v166, v212, v166
	v_add_f32_e32 v166, v213, v166
	v_add_f32_e32 v166, v214, v166
	v_add_f32_e32 v166, v215, v166
	v_add_f32_e32 v166, v216, v166
	v_add_f32_e32 v166, v217, v166
	v_add_f32_e32 v166, v218, v166
	v_add_f32_e32 v166, v221, v166
	s_waitcnt lgkmcnt(9)
	v_mfma_f32_32x32x16_bf16 v[84:99], v[68:71], v[100:103], 0
	v_add_f32_e32 v166, v222, v166
	v_add_f32_e32 v166, v223, v166
	v_exp_f32_e32 v132, v141
	v_add_f32_e32 v166, v224, v166
	v_exp_f32_e32 v133, v142
	s_waitcnt lgkmcnt(8)
	v_mfma_f32_32x32x16_bf16 v[84:99], v[72:75], v[116:119], v[84:99]
	v_add_f32_e32 v166, v225, v166
	v_exp_f32_e32 v134, v143
	v_add_f32_e32 v166, v226, v166
	v_exp_f32_e32 v135, v144
	v_add_f32_e32 v166, v227, v166
	s_waitcnt lgkmcnt(7)
	v_mfma_f32_32x32x16_bf16 v[84:99], v[76:79], v[104:107], v[84:99]
	v_exp_f32_e32 v136, v145
	v_add_f32_e32 v166, v132, v166
	v_exp_f32_e32 v137, v146
	v_add_f32_e32 v166, v133, v166
	v_exp_f32_e32 v138, v147
	s_waitcnt lgkmcnt(6)
	v_mfma_f32_32x32x16_bf16 v[84:99], v[80:83], v[120:123], v[84:99]
	v_add_f32_e32 v166, v134, v166
	v_add_f32_e32 v166, v135, v166
	v_exp_f32_e32 v141, v203
	v_add_f32_e32 v166, v136, v166
	v_exp_f32_e32 v142, v204
	s_waitcnt lgkmcnt(5)
	v_mfma_f32_32x32x16_bf16 v[84:99], v[228:231], v[108:111], v[84:99]
	v_add_u32_e32 v254, s95, v190
	ds_read_b128 v[228:231], v254 offset:57344
	v_add_f32_e32 v166, v137, v166
	v_exp_f32_e32 v143, v205
	v_add_f32_e32 v166, v138, v166
	v_exp_f32_e32 v144, v206
	v_add_f32_e32 v166, v139, v166
	s_waitcnt lgkmcnt(5)
	v_mfma_f32_32x32x16_bf16 v[84:99], v[232:235], v[124:127], v[84:99]
	ds_read_b128 v[232:235], v254 offset:57472
	v_exp_f32_e32 v145, v207
	v_add_f32_e32 v166, v141, v166
	v_exp_f32_e32 v146, v208
	v_add_f32_e32 v166, v142, v166
	v_exp_f32_e32 v147, v209
	s_waitcnt lgkmcnt(5)
	v_mfma_f32_32x32x16_bf16 v[84:99], v[236:239], v[112:115], v[84:99]
	v_add_u32_e32 v254, s95, v191
	ds_read_b128 v[236:239], v254 offset:57344
	v_add_f32_e32 v166, v143, v166
	v_add_f32_e32 v166, v144, v166
	v_add_f32_e32 v166, v145, v166
	v_add_f32_e32 v166, v146, v166
	v_add_f32_e32 v166, v147, v166
	s_waitcnt lgkmcnt(5)
	v_mfma_f32_32x32x16_bf16 v[84:99], v[240:243], v[128:131], v[84:99]
	ds_read_b128 v[240:243], v254 offset:57472
	v_add_f32_e32 v219, v140, v166
	v_mov_b32_e32 v220, v219
	s_nop 1
	v_permlane32_swap_b32_e32 v219, v220
	s_waitcnt lgkmcnt(5)
	v_mfma_f32_32x32x16_bf16 v[68:83], v[246:249], v[100:103], 0
	v_add_u32_e32 v254, s95, v192
	ds_read_b128 v[246:249], v254 offset:57344
	v_cvt_pk_bf16_f32 v204, v210, v211
	v_cvt_pk_bf16_f32 v205, v212, v213
	v_cvt_pk_bf16_f32 v206, v214, v215
	v_cvt_pk_bf16_f32 v207, v216, v217
	s_waitcnt lgkmcnt(5)
	v_mfma_f32_32x32x16_bf16 v[68:83], v[250:253], v[116:119], v[68:83]
	ds_read_b128 v[250:253], v254 offset:57472
	v_cvt_pk_bf16_f32 v208, v218, v221
	v_cvt_pk_bf16_f32 v209, v222, v223
	v_cvt_pk_bf16_f32 v210, v224, v225
	v_cvt_pk_bf16_f32 v211, v226, v227
	s_waitcnt lgkmcnt(5)
	v_mfma_f32_32x32x16_bf16 v[68:83], v[228:231], v[104:107], v[68:83]
	v_cvt_pk_bf16_f32 v212, v132, v133
	v_cvt_pk_bf16_f32 v213, v134, v135
	v_cvt_pk_bf16_f32 v214, v136, v137
	v_cvt_pk_bf16_f32 v215, v138, v139
	s_waitcnt lgkmcnt(4)
; #define SBAR() __builtin_amdgcn_sched_barrier(0)
; __device__ __forceinline__ void finishSM(f32x16& p0, f32x16& p1, float alpha, float& l_reg, bf16x8& pa0, bf16x8& pa1, bf16x8& pa2, bf16x8& pa3) {
;   for (int r = 0; r < 16; ++r) p1[r] = __builtin_amdgcn_exp2f(p1[r]);
;   float ps = 0; for (int r = 0; r < 16; ++r) ps += p0[r]; for (int r = 0; r < 16; ++r) ps += p1[r];
;   { auto rr = __builtin_amdgcn_permlane32_swap(__float_as_uint(ps), __float_as_uint(ps), false, false);
;     ps = __uint_as_float(rr[0]) + __uint_as_float(rr[1]); }
;   l_reg = l_reg * alpha + ps;
;     ...
;   PK4(p0, 0, pa0); PK4(p0, 8, pa1); PK4(p1, 0, pa2); PK4(p1, 8, pa3);
;     ...
; }
; __device__ __forceinline__ void qkt(f32x16& p0, f32x16& p1, const u16* Ks, const bf16x8* qr, int r32, int hi) {
;   p0 = f32x16{}; p1 = f32x16{};
;   for (int d0 = 0; d0 < 8; ++d0) { int cb = (d0 * 16 + hi * 8) * 2;
;     bf16x8 b0 = *reinterpret_cast<const bf16x8*>((const char*)Ks + KSWZ(r32, cb));
;     bf16x8 b1 = *reinterpret_cast<const bf16x8*>((const char*)Ks + KSWZ(32 + r32, cb));
;     p0 = __builtin_amdgcn_mfma_f32_32x32x16_bf16(b0, qr[d0], p0, 0, 0, 0);
;     p1 = __builtin_amdgcn_mfma_f32_32x32x16_bf16(b1, qr[d0], p1, 0, 0, 0); }
; }
; template <int D0> __device__ __forceinline__ void pv_one(f32x16& od, int vb, bf16x8 pa0, bf16x8 pa1, bf16x8 pa2, bf16x8 pa3) {
;   const s16x4 l0 = tr_read<v_rd_off(D0, 0, 0)>(vb), h0 = tr_read<v_rd_off(D0, 0, 1)>(vb), l1 = tr_read<v_rd_off(D0, 1, 0)>(vb), h1 = tr_read<v_rd_off(D0, 1, 1)>(vb);
;   const s16x4 l2 = tr_read<v_rd_off(D0, 2, 0)>(vb), h2 = tr_read<v_rd_off(D0, 2, 1)>(vb), l3 = tr_read<v_rd_off(D0, 3, 0)>(vb), h3 = tr_read<v_rd_off(D0, 3, 1)>(vb);
;   asm volatile("s_waitcnt lgkmcnt(0)" ::: "memory"); SBAR();
;     ...
;   od = __builtin_amdgcn_mfma_f32_32x32x16_bf16(pa0, PK(l0, h0), od, 0, 0, 0);
;   od = __builtin_amdgcn_mfma_f32_32x32x16_bf16(pa1, PK(l1, h1), od, 0, 0, 0);
;   od = __builtin_amdgcn_mfma_f32_32x32x16_bf16(pa2, PK(l2, h2), od, 0, 0, 0);
;   od = __builtin_amdgcn_mfma_f32_32x32x16_bf16(pa3, PK(l3, h3), od, 0, 0, 0);
;     ...
; }
; __device__ __forceinline__ void pv_d0(f32x16* o, int vb, bf16x8 pa0, bf16x8 pa1, bf16x8 pa2, bf16x8 pa3) {
;   pv_one<0>(o[0], vb, pa0, pa1, pa2, pa3); pv_one<1>(o[1], vb, pa0, pa1, pa2, pa3); pv_one<2>(o[2], vb, pa0, pa1, pa2, pa3); pv_one<3>(o[3], vb, pa0, pa1, pa2, pa3);
	v_mfma_f32_32x32x16_bf16 v[68:83], v[232:235], v[120:123], v[68:83]
	v_cvt_pk_bf16_f32 v222, v141, v142
	v_cvt_pk_bf16_f32 v223, v143, v144
	v_cvt_pk_bf16_f32 v224, v145, v146
	v_cvt_pk_bf16_f32 v225, v147, v140
	s_waitcnt lgkmcnt(3)
	v_mfma_f32_32x32x16_bf16 v[68:83], v[236:239], v[108:111], v[68:83]
	s_nop 0
	v_permlane32_swap_b32_e32 v204, v206
	v_permlane32_swap_b32_e32 v205, v207
	v_permlane32_swap_b32_e32 v208, v210
	s_waitcnt lgkmcnt(2)
	v_mfma_f32_32x32x16_bf16 v[68:83], v[240:243], v[124:127], v[68:83]
	v_permlane32_swap_b32_e32 v209, v211
	v_permlane32_swap_b32_e32 v212, v214
	v_permlane32_swap_b32_e32 v213, v215
	v_permlane32_swap_b32_e32 v222, v224
	s_waitcnt lgkmcnt(1)
	v_mfma_f32_32x32x16_bf16 v[68:83], v[246:249], v[112:115], v[68:83]
	v_permlane32_swap_b32_e32 v223, v225
	s_min_u32 s7, s16, s90
	s_add_i32 s7, s7, s88
	s_lshl_b32 s7, s7, 6
	s_waitcnt lgkmcnt(0)
	v_mfma_f32_32x32x16_bf16 v[68:83], v[250:253], v[128:131], v[68:83]
	v_add_u32_e32 v244, s7, v167
	v_add_u32_e32 v245, s7, v185
	v_lshl_or_b32 v244, v244, 8, v182
	v_lshl_or_b32 v245, v245, 8, v182
	global_load_dwordx4 v[136:139], v244, s[58:59]
	global_load_dwordx4 v[132:135], v245, s[58:59]
	global_load_dwordx4 v[144:147], v244, s[64:65]
	global_load_dwordx4 v[140:143], v245, s[64:65]
	v_add_u32_e32 v254, s93, v197
	ds_read_b64_tr_b16 v[230:231], v254 offset:0
	ds_read_b64_tr_b16 v[232:233], v254 offset:2048
	ds_read_b64_tr_b16 v[234:235], v254 offset:4096
	ds_read_b64_tr_b16 v[236:237], v254 offset:6144
	ds_read_b64_tr_b16 v[238:239], v254 offset:8192
	ds_read_b64_tr_b16 v[240:241], v254 offset:10240
	ds_read_b64_tr_b16 v[242:243], v254 offset:12288
	ds_read_b64_tr_b16 v[244:245], v254 offset:14336
	ds_read_b64_tr_b16 v[246:247], v254 offset:512
	ds_read_b64_tr_b16 v[248:249], v254 offset:2560
	s_waitcnt lgkmcnt(6)
	v_mfma_f32_32x32x16_bf16 v[52:67], v[204:207], v[230:233], v[52:67]
	ds_read_b64_tr_b16 v[250:251], v254 offset:4608
	ds_read_b64_tr_b16 v[252:253], v254 offset:6656
	v_max_f32_e32 v166, v85, v85
	v_max_f32_e32 v203, v84, v84
	v_mfma_f32_32x32x16_bf16 v[52:67], v[208:211], v[234:237], v[52:67]
	ds_read_b64_tr_b16 v[230:231], v254 offset:8704
	ds_read_b64_tr_b16 v[232:233], v254 offset:10752
	v_max_f32_e32 v166, v203, v166
	v_max3_f32 v166, v166, v86, v87
	s_waitcnt lgkmcnt(6)
	v_mfma_f32_32x32x16_bf16 v[52:67], v[212:215], v[238:241], v[52:67]
	ds_read_b64_tr_b16 v[234:235], v254 offset:12800
	ds_read_b64_tr_b16 v[236:237], v254 offset:14848
	v_max3_f32 v166, v166, v88, v89
	v_max3_f32 v166, v166, v90, v91
	v_mfma_f32_32x32x16_bf16 v[52:67], v[222:225], v[242:245], v[52:67]
	ds_read_b64_tr_b16 v[238:239], v254 offset:1024
	ds_read_b64_tr_b16 v[240:241], v254 offset:3072
	v_max3_f32 v166, v166, v92, v93
	v_max3_f32 v166, v166, v94, v95
	s_waitcnt lgkmcnt(6)
	v_mfma_f32_32x32x16_bf16 v[36:51], v[204:207], v[246:249], v[36:51]
	ds_read_b64_tr_b16 v[242:243], v254 offset:5120
	ds_read_b64_tr_b16 v[244:245], v254 offset:7168
	v_max3_f32 v166, v166, v96, v97
	v_max3_f32 v166, v166, v98, v99
	v_mfma_f32_32x32x16_bf16 v[36:51], v[208:211], v[250:253], v[36:51]
	ds_read_b64_tr_b16 v[246:247], v254 offset:9216
	ds_read_b64_tr_b16 v[248:249], v254 offset:11264
	v_max3_f32 v166, v166, v68, v69
	v_max3_f32 v166, v166, v70, v71
	s_waitcnt lgkmcnt(6)
	v_mfma_f32_32x32x16_bf16 v[36:51], v[212:215], v[230:233], v[36:51]
	ds_read_b64_tr_b16 v[250:251], v254 offset:13312
	ds_read_b64_tr_b16 v[252:253], v254 offset:15360
	v_max3_f32 v166, v166, v72, v73
	v_mfma_f32_32x32x16_bf16 v[36:51], v[222:225], v[234:237], v[36:51]
	ds_read_b64_tr_b16 v[230:231], v254 offset:1536
	ds_read_b64_tr_b16 v[232:233], v254 offset:3584
	v_max3_f32 v166, v166, v74, v75
	s_waitcnt lgkmcnt(6)
	v_mfma_f32_32x32x16_bf16 v[20:35], v[204:207], v[238:241], v[20:35]
	ds_read_b64_tr_b16 v[234:235], v254 offset:5632
	ds_read_b64_tr_b16 v[236:237], v254 offset:7680
	v_max3_f32 v166, v166, v76, v77
	v_mfma_f32_32x32x16_bf16 v[20:35], v[208:211], v[242:245], v[20:35]
	ds_read_b64_tr_b16 v[238:239], v254 offset:9728
	ds_read_b64_tr_b16 v[240:241], v254 offset:11776
	v_max3_f32 v166, v166, v78, v79
	s_waitcnt lgkmcnt(6)
	v_mfma_f32_32x32x16_bf16 v[20:35], v[212:215], v[246:249], v[20:35]
	ds_read_b64_tr_b16 v[242:243], v254 offset:13824
	ds_read_b64_tr_b16 v[244:245], v254 offset:15872
	v_max3_f32 v166, v166, v80, v81
	v_mfma_f32_32x32x16_bf16 v[20:35], v[222:225], v[250:253], v[20:35]
	v_max3_f32 v166, v166, v82, v83
	s_waitcnt lgkmcnt(4)
	v_mfma_f32_32x32x16_bf16 v[4:19], v[204:207], v[230:233], v[4:19]
	v_mfma_f32_32x32x16_bf16 v[4:19], v[208:211], v[234:237], v[4:19]
	s_waitcnt lgkmcnt(0)
	v_mfma_f32_32x32x16_bf16 v[4:19], v[212:215], v[238:241], v[4:19]
	v_mov_b32_e32 v203, v166
	s_nop 1
	v_permlane32_swap_b32_e32 v166, v203
	v_max_f32_e32 v203, v203, v203
	v_max_f32_e32 v166, v166, v166
	v_max_f32_e32 v166, v166, v203
	v_sub_f32_e32 v203, v166, v2
	v_cmp_ge_f32_e32 vcc, s74, v203
	v_max_f32_e32 v203, v2, v2
	v_max_f32_e32 v166, v203, v166
	v_sub_f32_e32 v203, v2, v166
	v_mul_f32_e32 v203, 0x3e0293ee, v203
	v_mfma_f32_32x32x16_bf16 v[4:19], v[222:225], v[242:245], v[4:19]
	v_exp_f32_e32 v203, v203
	s_cmp_eq_u64 vcc, exec
	s_cselect_b64 s[6:7], -1, 0
	s_add_i32 s30, s94, 0
	v_cndmask_b32_e64 v221, v203, 1.0, s[6:7]
	v_add_u32_e32 v203, s30, v184
	s_waitcnt vmcnt(4)
	ds_write_b128 v203, v[152:155]
	v_add_u32_e32 v152, s30, v186
	ds_write_b128 v152, v[148:151]
	v_add_u32_e32 v148, s30, v187
	ds_write_b128 v148, v[160:163] offset:49152
	v_add_u32_e32 v148, s30, v188
	v_cmp_gt_f32_e32 vcc, 1.0, v221
	s_waitcnt vmcnt(4)
	ds_write_b128 v148, v[156:159] offset:49152
	s_cbranch_vccz .LBB0_482
	s_and_saveexec_b64 s[66:67], s[4:5]
	ds_write_b32 v183, v221 offset:128
	s_or_b64 exec, exec, s[66:67]
	s_waitcnt lgkmcnt(0)
	v_add_u32_e32 v160, v181, v180
	ds_read_b128 v[148:151], v160 offset:224
	ds_read_b128 v[152:155], v160 offset:192
	ds_read_b128 v[156:159], v160 offset:160
	ds_read_b128 v[160:163], v160 offset:128
	s_waitcnt lgkmcnt(3)
	v_pk_mul_f32 v[64:65], v[64:65], v[148:149]
	s_waitcnt lgkmcnt(2)
	v_pk_mul_f32 v[60:61], v[60:61], v[152:153]
	s_waitcnt lgkmcnt(1)
	v_pk_mul_f32 v[56:57], v[56:57], v[156:157]
	v_pk_mul_f32 v[66:67], v[66:67], v[150:151]
	v_pk_mul_f32 v[62:63], v[62:63], v[154:155]
	v_pk_mul_f32 v[58:59], v[58:59], v[158:159]
	s_waitcnt lgkmcnt(0)
	v_pk_mul_f32 v[54:55], v[54:55], v[162:163]
	v_pk_mul_f32 v[52:53], v[52:53], v[160:161]
	v_pk_mul_f32 v[48:49], v[48:49], v[148:149]
	v_pk_mul_f32 v[44:45], v[44:45], v[152:153]
	v_pk_mul_f32 v[40:41], v[40:41], v[156:157]
	v_pk_mul_f32 v[50:51], v[50:51], v[150:151]
	v_pk_mul_f32 v[46:47], v[46:47], v[154:155]
	v_pk_mul_f32 v[42:43], v[42:43], v[158:159]
	v_pk_mul_f32 v[38:39], v[38:39], v[162:163]
	v_pk_mul_f32 v[36:37], v[36:37], v[160:161]
	v_pk_mul_f32 v[32:33], v[32:33], v[148:149]
	v_pk_mul_f32 v[28:29], v[28:29], v[152:153]
	v_pk_mul_f32 v[24:25], v[24:25], v[156:157]
	v_pk_mul_f32 v[34:35], v[34:35], v[150:151]
	v_pk_mul_f32 v[30:31], v[30:31], v[154:155]
	v_pk_mul_f32 v[26:27], v[26:27], v[158:159]
	v_pk_mul_f32 v[22:23], v[22:23], v[162:163]
	v_pk_mul_f32 v[20:21], v[20:21], v[160:161]
	v_pk_mul_f32 v[16:17], v[16:17], v[148:149]
	v_pk_mul_f32 v[12:13], v[12:13], v[152:153]
	v_pk_mul_f32 v[8:9], v[8:9], v[156:157]
	v_pk_mul_f32 v[18:19], v[18:19], v[150:151]
	v_pk_mul_f32 v[14:15], v[14:15], v[154:155]
	v_pk_mul_f32 v[10:11], v[10:11], v[158:159]
	v_pk_mul_f32 v[6:7], v[6:7], v[162:163]
	v_pk_mul_f32 v[4:5], v[4:5], v[160:161]

; #define SBAR() __builtin_amdgcn_sched_barrier(0)
; #define QKT(P0, P1, KS) do { if (MODE == 1) qkt_lds(P0, P1, KS, qs, r32, hi); else qkt(P0, P1, KS, qr, r32, hi); } while (0)
; __device__ __forceinline__ void finishSM(f32x16& p0, f32x16& p1, float alpha, float& l_reg, bf16x8& pa0, bf16x8& pa1, bf16x8& pa2, bf16x8& pa3) {
;   for (int r = 0; r < 16; ++r) p1[r] = __builtin_amdgcn_exp2f(p1[r]);
;   float ps = 0; for (int r = 0; r < 16; ++r) ps += p0[r]; for (int r = 0; r < 16; ++r) ps += p1[r];
;   { auto rr = __builtin_amdgcn_permlane32_swap(__float_as_uint(ps), __float_as_uint(ps), false, false);
;     ps = __uint_as_float(rr[0]) + __uint_as_float(rr[1]); }
;   l_reg = l_reg * alpha + ps;
;     ...
;   PK4(p0, 0, pa0); PK4(p0, 8, pa1); PK4(p1, 0, pa2); PK4(p1, 8, pa3);
;     ...
; }
; __device__ __forceinline__ void qkt(f32x16& p0, f32x16& p1, const u16* Ks, const bf16x8* qr, int r32, int hi) {
;   p0 = f32x16{}; p1 = f32x16{};
;   for (int d0 = 0; d0 < 8; ++d0) { int cb = (d0 * 16 + hi * 8) * 2;
;     bf16x8 b0 = *reinterpret_cast<const bf16x8*>((const char*)Ks + KSWZ(r32, cb));
;     bf16x8 b1 = *reinterpret_cast<const bf16x8*>((const char*)Ks + KSWZ(32 + r32, cb));
;     p0 = __builtin_amdgcn_mfma_f32_32x32x16_bf16(b0, qr[d0], p0, 0, 0, 0);
;     p1 = __builtin_amdgcn_mfma_f32_32x32x16_bf16(b1, qr[d0], p1, 0, 0, 0); }
; }
; template <int MODE> ...
;     ...
;     for (int j = 1; j + 1 < NT; j += 2) {
;       const int s0_ = sj, s1_ = sj == 2 ? 0 : sj + 1, s2_ = s1_ == 2 ? 0 : s1_ + 1;
;       SBAR(); QKT(pB0, pB1, (u16*)((char*)K_lds + s0_ * SHM_K));
;       finishSM(pA0, pA1, alA, l_reg, pa0, pa1, pa2, pa3); SBAR();
;       { const int tn = (j + 2 < NT) ? j + 2 : NT - 1; SLOAD(SO, tn); } SBAR();
;       pv_d0(o, vb0 + s2_ * (int)SHM_V, pa0, pa1, pa2, pa3); partialSM(pB0, pB1, m_reg, mnB, alB);
.Lstg_loop:
	s_add_i32 s7, s89, 1
	s_cmp_lg_u32 s89, 2
	s_cselect_b32 s66, s7, 0
	s_add_i32 s7, s66, 1
	s_cmp_lg_u32 s66, 2
	s_mov_b32 s6, s89
	s_cselect_b32 s89, s7, 0
	s_lshl_b32 s93, s6, 14
	s_add_i32 s6, s93, 0
	v_add_u32_e32 v254, s6, v189
	ds_read_b128 v[68:71], v254 offset:49152
	ds_read_b128 v[72:75], v254 offset:49280
	v_add_u32_e32 v254, s6, v190
	ds_read_b128 v[76:79], v254 offset:49152
	ds_read_b128 v[80:83], v254 offset:49280
	v_add_u32_e32 v254, s6, v191
	ds_read_b128 v[220:223], v254 offset:49152
	ds_read_b128 v[224:227], v254 offset:49280
	v_add_u32_e32 v254, s6, v192
	ds_read_b128 v[228:231], v254 offset:49152
	ds_read_b128 v[232:235], v254 offset:49280
	v_add_u32_e32 v254, s6, v189
	ds_read_b128 v[236:239], v254 offset:57344
	ds_read_b128 v[240:243], v254 offset:57472
	v_exp_f32_e32 v160, v160
	v_exp_f32_e32 v161, v161
	v_exp_f32_e32 v158, v158
	v_exp_f32_e32 v159, v159
	v_exp_f32_e32 v156, v156
	v_exp_f32_e32 v157, v157
	v_exp_f32_e32 v154, v154
	v_exp_f32_e32 v155, v155
	v_exp_f32_e32 v152, v152
	v_exp_f32_e32 v153, v153
	v_exp_f32_e32 v150, v150
	v_exp_f32_e32 v151, v151
	s_waitcnt lgkmcnt(9)
	v_mfma_f32_32x32x16_bf16 v[84:99], v[68:71], v[100:103], 0
	v_exp_f32_e32 v148, v148
	v_exp_f32_e32 v149, v149
	v_exp_f32_e32 v2, v162
	v_exp_f32_e32 v162, v163
	v_add_f32_e32 v163, 0, v216
	s_waitcnt lgkmcnt(8)
	v_mfma_f32_32x32x16_bf16 v[84:99], v[72:75], v[116:119], v[84:99]
	v_add_f32_e32 v163, v218, v163
	v_add_f32_e32 v163, v214, v163
	v_add_f32_e32 v163, v217, v163
	v_add_f32_e32 v163, v213, v163
	v_add_f32_e32 v163, v215, v163
	s_waitcnt lgkmcnt(7)
	v_mfma_f32_32x32x16_bf16 v[84:99], v[76:79], v[104:107], v[84:99]
	v_add_f32_e32 v163, v211, v163
	v_add_f32_e32 v163, v212, v163
	v_add_f32_e32 v163, v208, v163
	v_add_f32_e32 v163, v210, v163
	v_add_f32_e32 v163, v207, v163
	s_waitcnt lgkmcnt(6)
	v_mfma_f32_32x32x16_bf16 v[84:99], v[80:83], v[120:123], v[84:99]
	v_add_f32_e32 v163, v209, v163
	v_add_f32_e32 v163, v204, v163
	v_add_f32_e32 v163, v206, v163
	v_add_f32_e32 v163, v203, v163
	v_add_f32_e32 v163, v205, v163
	s_waitcnt lgkmcnt(5)
	v_mfma_f32_32x32x16_bf16 v[84:99], v[220:223], v[108:111], v[84:99]
	v_add_u32_e32 v254, s6, v190
	ds_read_b128 v[220:223], v254 offset:57344
	v_add_f32_e32 v163, v2, v163
	v_add_f32_e32 v163, v162, v163
	v_add_f32_e32 v163, v160, v163
	v_add_f32_e32 v163, v161, v163
	v_add_f32_e32 v163, v158, v163
	s_waitcnt lgkmcnt(5)
	v_mfma_f32_32x32x16_bf16 v[84:99], v[224:227], v[124:127], v[84:99]
	ds_read_b128 v[224:227], v254 offset:57472
	v_add_f32_e32 v163, v159, v163
	v_add_f32_e32 v163, v156, v163
	v_add_f32_e32 v163, v157, v163
	v_add_f32_e32 v163, v154, v163
	v_add_f32_e32 v163, v155, v163
	s_waitcnt lgkmcnt(5)
	v_mfma_f32_32x32x16_bf16 v[84:99], v[228:231], v[112:115], v[84:99]
	v_add_u32_e32 v254, s6, v191
	ds_read_b128 v[228:231], v254 offset:57344
	v_add_f32_e32 v163, v152, v163
	v_add_f32_e32 v163, v153, v163
	v_add_f32_e32 v163, v150, v163
	v_add_f32_e32 v163, v151, v163
	s_waitcnt lgkmcnt(5)
	v_mfma_f32_32x32x16_bf16 v[84:99], v[232:235], v[128:131], v[84:99]
	ds_read_b128 v[232:235], v254 offset:57472
	v_add_f32_e32 v163, v148, v163
	v_add_f32_e32 v200, v149, v163
	v_mov_b32_e32 v201, v200
	v_cvt_pk_bf16_f32 v216, v216, v218
	s_waitcnt lgkmcnt(5)
	v_mfma_f32_32x32x16_bf16 v[68:83], v[236:239], v[100:103], 0
	v_add_u32_e32 v254, s6, v192
	ds_read_b128 v[236:239], v254 offset:57344
	v_cvt_pk_bf16_f32 v217, v214, v217
	v_cvt_pk_bf16_f32 v218, v213, v215
	v_cvt_pk_bf16_f32 v219, v211, v212
	v_cvt_pk_bf16_f32 v208, v208, v210
	s_waitcnt lgkmcnt(5)
	v_mfma_f32_32x32x16_bf16 v[68:83], v[240:243], v[116:119], v[68:83]
	ds_read_b128 v[240:243], v254 offset:57472
	v_cvt_pk_bf16_f32 v209, v207, v209
	v_cvt_pk_bf16_f32 v210, v204, v206
	v_cvt_pk_bf16_f32 v211, v203, v205
	v_cvt_pk_bf16_f32 v202, v2, v162
	s_waitcnt lgkmcnt(5)
	v_mfma_f32_32x32x16_bf16 v[68:83], v[220:223], v[104:107], v[68:83]
	v_cvt_pk_bf16_f32 v203, v160, v161
	v_cvt_pk_bf16_f32 v204, v158, v159
	v_permlane32_swap_b32_e32 v200, v201
	v_cvt_pk_bf16_f32 v205, v156, v157
	s_waitcnt lgkmcnt(4)
	v_mfma_f32_32x32x16_bf16 v[68:83], v[224:227], v[120:123], v[68:83]
	v_permlane32_swap_b32_e32 v202, v204
	v_cvt_pk_bf16_f32 v212, v154, v155
	v_cvt_pk_bf16_f32 v213, v152, v153
	v_cvt_pk_bf16_f32 v214, v150, v151
	s_waitcnt lgkmcnt(3)
	v_mfma_f32_32x32x16_bf16 v[68:83], v[228:231], v[108:111], v[68:83]
	v_cvt_pk_bf16_f32 v215, v148, v149
	v_permlane32_swap_b32_e32 v216, v218
	v_permlane32_swap_b32_e32 v217, v219
	v_permlane32_swap_b32_e32 v208, v210
	s_waitcnt lgkmcnt(2)
	v_mfma_f32_32x32x16_bf16 v[68:83], v[232:235], v[124:127], v[68:83]
	v_permlane32_swap_b32_e32 v209, v211
	v_permlane32_swap_b32_e32 v203, v205
	v_permlane32_swap_b32_e32 v212, v214
	v_permlane32_swap_b32_e32 v213, v215
	s_waitcnt lgkmcnt(1)
	v_mfma_f32_32x32x16_bf16 v[68:83], v[236:239], v[112:115], v[68:83]
	s_add_i32 s91, s16, -1
	s_min_u32 s7, s91, s90
	s_add_i32 s7, s7, s88
	s_lshl_b32 s7, s7, 6
	s_waitcnt lgkmcnt(0)
	v_mfma_f32_32x32x16_bf16 v[68:83], v[240:243], v[128:131], v[68:83]
	v_add_u32_e32 v244, s7, v167
	v_add_u32_e32 v245, s7, v185
	v_lshl_or_b32 v244, v244, 8, v182
	v_lshl_or_b32 v245, v245, 8, v182
	global_load_dwordx4 v[152:155], v244, s[58:59]
	global_load_dwordx4 v[148:151], v245, s[58:59]
	global_load_dwordx4 v[160:163], v244, s[64:65]
	global_load_dwordx4 v[156:159], v245, s[64:65]
	s_lshl_b32 s94, s89, 14
	v_add_u32_e32 v254, s94, v197
	ds_read_b64_tr_b16 v[220:221], v254 offset:0
	ds_read_b64_tr_b16 v[222:223], v254 offset:2048
	ds_read_b64_tr_b16 v[224:225], v254 offset:4096
	ds_read_b64_tr_b16 v[226:227], v254 offset:6144
	ds_read_b64_tr_b16 v[228:229], v254 offset:8192
	ds_read_b64_tr_b16 v[230:231], v254 offset:10240
	ds_read_b64_tr_b16 v[232:233], v254 offset:12288
	ds_read_b64_tr_b16 v[234:235], v254 offset:14336
	ds_read_b64_tr_b16 v[236:237], v254 offset:512
	ds_read_b64_tr_b16 v[238:239], v254 offset:2560
	s_waitcnt lgkmcnt(6)
; #define SBAR() __builtin_amdgcn_sched_barrier(0)
; #define SWRITE(b, i) do { *(bf16x8*)((char*)V_lds + (b) * SHM_V + vst0) = sr_[i].vs0;          \
;     *(bf16x8*)((char*)V_lds + (b) * SHM_V + vst1) = sr_[i].vs1; int kc = sc * 2;               \
;     *(bf16x8*)((char*)K_lds + (b) * SHM_K + KSWZ(sr, kc)) = sr_[i].ks0;                       \
;     *(bf16x8*)((char*)K_lds + (b) * SHM_K + KSWZ(32 + sr, kc)) = sr_[i].ks1; } while (0)
; #define SWAIT() do { if (SD == 2) asm volatile("s_waitcnt vmcnt(4)" ::: "memory"); else asm volatile("s_waitcnt vmcnt(0)" ::: "memory"); } while (0)
; #define RESC(a) do { if (__any((a) < 1.f)) { if (hi == 0) al_l[r32] = (a); asm volatile("s_waitcnt lgkmcnt(0)" ::: "memory"); \
;     for (int d = 0; d < 4; ++d) for (int r = 0; r < 16; ++r) o[d][r] *= al_l[crow(r, hi)]; } } while (0)
; template <int D0> __device__ __forceinline__ void pv_one(f32x16& od, int vb, bf16x8 pa0, bf16x8 pa1, bf16x8 pa2, bf16x8 pa3) {
;   const s16x4 l0 = tr_read<v_rd_off(D0, 0, 0)>(vb), h0 = tr_read<v_rd_off(D0, 0, 1)>(vb), l1 = tr_read<v_rd_off(D0, 1, 0)>(vb), h1 = tr_read<v_rd_off(D0, 1, 1)>(vb);
;   const s16x4 l2 = tr_read<v_rd_off(D0, 2, 0)>(vb), h2 = tr_read<v_rd_off(D0, 2, 1)>(vb), l3 = tr_read<v_rd_off(D0, 3, 0)>(vb), h3 = tr_read<v_rd_off(D0, 3, 1)>(vb);
;   asm volatile("s_waitcnt lgkmcnt(0)" ::: "memory"); SBAR();
;     ...
;   od = __builtin_amdgcn_mfma_f32_32x32x16_bf16(pa0, PK(l0, h0), od, 0, 0, 0);
;   od = __builtin_amdgcn_mfma_f32_32x32x16_bf16(pa1, PK(l1, h1), od, 0, 0, 0);
;   od = __builtin_amdgcn_mfma_f32_32x32x16_bf16(pa2, PK(l2, h2), od, 0, 0, 0);
;   od = __builtin_amdgcn_mfma_f32_32x32x16_bf16(pa3, PK(l3, h3), od, 0, 0, 0);
;     ...
; }
; __device__ __forceinline__ void pv_d0(f32x16* o, int vb, bf16x8 pa0, bf16x8 pa1, bf16x8 pa2, bf16x8 pa3) {
;   pv_one<0>(o[0], vb, pa0, pa1, pa2, pa3); pv_one<1>(o[1], vb, pa0, pa1, pa2, pa3); pv_one<2>(o[2], vb, pa0, pa1, pa2, pa3); pv_one<3>(o[3], vb, pa0, pa1, pa2, pa3);
; template <int MODE> ...
;     ...
;       SWAIT(); SWRITE(s1_, SE);
;       RESC(alB); __syncthreads();
	v_mfma_f32_32x32x16_bf16 v[52:67], v[216:219], v[220:223], v[52:67]
	ds_read_b64_tr_b16 v[240:241], v254 offset:4608
	ds_read_b64_tr_b16 v[242:243], v254 offset:6656
	v_mfma_f32_32x32x16_bf16 v[52:67], v[208:211], v[224:227], v[52:67]
	ds_read_b64_tr_b16 v[220:221], v254 offset:8704
	ds_read_b64_tr_b16 v[222:223], v254 offset:10752
	s_waitcnt lgkmcnt(6)
	v_mfma_f32_32x32x16_bf16 v[52:67], v[202:205], v[228:231], v[52:67]
	ds_read_b64_tr_b16 v[224:225], v254 offset:12800
	ds_read_b64_tr_b16 v[226:227], v254 offset:14848
	v_mfma_f32_32x32x16_bf16 v[52:67], v[212:215], v[232:235], v[52:67]
	ds_read_b64_tr_b16 v[228:229], v254 offset:1024
	ds_read_b64_tr_b16 v[230:231], v254 offset:3072
	s_waitcnt lgkmcnt(6)
	v_mfma_f32_32x32x16_bf16 v[36:51], v[216:219], v[236:239], v[36:51]
	ds_read_b64_tr_b16 v[232:233], v254 offset:5120
	ds_read_b64_tr_b16 v[234:235], v254 offset:7168
	v_mfma_f32_32x32x16_bf16 v[36:51], v[208:211], v[240:243], v[36:51]
	ds_read_b64_tr_b16 v[236:237], v254 offset:9216
	ds_read_b64_tr_b16 v[238:239], v254 offset:11264
	s_waitcnt lgkmcnt(6)
	v_mfma_f32_32x32x16_bf16 v[36:51], v[202:205], v[220:223], v[36:51]
	ds_read_b64_tr_b16 v[240:241], v254 offset:13312
	ds_read_b64_tr_b16 v[242:243], v254 offset:15360
	v_mfma_f32_32x32x16_bf16 v[36:51], v[212:215], v[224:227], v[36:51]
	ds_read_b64_tr_b16 v[220:221], v254 offset:1536
	ds_read_b64_tr_b16 v[222:223], v254 offset:3584
	s_waitcnt lgkmcnt(6)
	v_mfma_f32_32x32x16_bf16 v[20:35], v[216:219], v[228:231], v[20:35]
	ds_read_b64_tr_b16 v[224:225], v254 offset:5632
	ds_read_b64_tr_b16 v[226:227], v254 offset:7680
	v_mfma_f32_32x32x16_bf16 v[20:35], v[208:211], v[232:235], v[20:35]
	ds_read_b64_tr_b16 v[228:229], v254 offset:9728
	ds_read_b64_tr_b16 v[230:231], v254 offset:11776
	s_waitcnt lgkmcnt(6)
	v_mfma_f32_32x32x16_bf16 v[20:35], v[202:205], v[236:239], v[20:35]
	ds_read_b64_tr_b16 v[232:233], v254 offset:13824
	ds_read_b64_tr_b16 v[234:235], v254 offset:15872
	v_mfma_f32_32x32x16_bf16 v[20:35], v[212:215], v[240:243], v[20:35]
	s_waitcnt lgkmcnt(4)
	v_mfma_f32_32x32x16_bf16 v[4:19], v[216:219], v[220:223], v[4:19]
	s_waitcnt vmcnt(4)
	v_mfma_f32_32x32x16_bf16 v[4:19], v[208:211], v[224:227], v[4:19]
	s_waitcnt lgkmcnt(0)
	v_mfma_f32_32x32x16_bf16 v[4:19], v[202:205], v[228:231], v[4:19]
	v_mfma_f32_32x32x16_bf16 v[4:19], v[212:215], v[232:235], v[4:19]
	s_lshl_b32 s92, s66, 14
	s_add_i32 s95, s92, 0
	v_add_u32_e32 v203, s95, v184
	ds_write_b128 v203, v[136:139]
	v_add_u32_e32 v136, s95, v186
	ds_write_b128 v136, v[132:135]
	v_add_u32_e32 v132, s95, v187
	ds_write_b128 v132, v[144:147] offset:49152
	v_add_u32_e32 v132, s95, v188
	s_waitcnt vmcnt(4)
	ds_write_b128 v132, v[140:143] offset:49152
	s_waitcnt lgkmcnt(0)
	s_barrier
	v_max_f32_e32 v2, v85, v85
	v_max_f32_e32 v202, v84, v84
	v_max_f32_e32 v2, v202, v2
	v_max3_f32 v2, v2, v86, v87
	v_max3_f32 v2, v2, v88, v89
	v_max3_f32 v2, v2, v90, v91
	v_max3_f32 v2, v2, v92, v93
	v_max3_f32 v2, v2, v94, v95
	v_max3_f32 v2, v2, v96, v97
	v_max3_f32 v2, v2, v98, v99
	v_max3_f32 v2, v2, v68, v69
	v_max3_f32 v2, v2, v70, v71
	v_max3_f32 v2, v2, v72, v73
	v_max3_f32 v2, v2, v74, v75
	v_max3_f32 v2, v2, v76, v77
	v_max3_f32 v2, v2, v78, v79
	v_max3_f32 v2, v2, v80, v81
	v_max3_f32 v2, v2, v82, v83
	v_mov_b32_e32 v202, v2
	s_nop 1
	v_permlane32_swap_b32_e32 v2, v202
	v_max_f32_e32 v202, v202, v202
	v_max_f32_e32 v2, v2, v2
	v_max_f32_e32 v2, v2, v202
	v_sub_f32_e32 v202, v2, v166
	v_cmp_ge_f32_e32 vcc, s74, v202
	v_max_f32_e32 v202, v166, v166
	v_max_f32_e32 v2, v202, v2
	v_sub_f32_e32 v202, v166, v2
	s_cmp_eq_u64 vcc, exec
	v_mul_f32_e32 v202, 0x3e0293ee, v202
	s_cselect_b64 s[6:7], -1, 0
	v_exp_f32_e32 v202, v202
	s_nop 0
	v_cndmask_b32_e64 v202, v202, 1.0, s[6:7]
	v_cmp_gt_f32_e32 vcc, 1.0, v202
	s_cbranch_vccz .Lstg_r1
	s_and_saveexec_b64 s[66:67], s[4:5]
	ds_write_b32 v183, v202 offset:128
	s_or_b64 exec, exec, s[66:67]
	s_waitcnt lgkmcnt(0)
	v_add_u32_e32 v144, v181, v180
	ds_read_b128 v[132:135], v144 offset:224
	ds_read_b128 v[136:139], v144 offset:192
	ds_read_b128 v[140:143], v144 offset:160
	ds_read_b128 v[144:147], v144 offset:128
	s_waitcnt lgkmcnt(3)
	v_pk_mul_f32 v[64:65], v[64:65], v[132:133]
	s_waitcnt lgkmcnt(2)
	v_pk_mul_f32 v[60:61], v[60:61], v[136:137]
	s_waitcnt lgkmcnt(1)
	v_pk_mul_f32 v[56:57], v[56:57], v[140:141]
	v_pk_mul_f32 v[66:67], v[66:67], v[134:135]
	v_pk_mul_f32 v[62:63], v[62:63], v[138:139]
	v_pk_mul_f32 v[58:59], v[58:59], v[142:143]
	s_waitcnt lgkmcnt(0)
	v_pk_mul_f32 v[54:55], v[54:55], v[146:147]
	v_pk_mul_f32 v[52:53], v[52:53], v[144:145]
	v_pk_mul_f32 v[48:49], v[48:49], v[132:133]
	v_pk_mul_f32 v[44:45], v[44:45], v[136:137]
	v_pk_mul_f32 v[40:41], v[40:41], v[140:141]
	v_pk_mul_f32 v[50:51], v[50:51], v[134:135]
	v_pk_mul_f32 v[46:47], v[46:47], v[138:139]
	v_pk_mul_f32 v[42:43], v[42:43], v[142:143]
	v_pk_mul_f32 v[38:39], v[38:39], v[146:147]
	v_pk_mul_f32 v[36:37], v[36:37], v[144:145]
	v_pk_mul_f32 v[32:33], v[32:33], v[132:133]
	v_pk_mul_f32 v[28:29], v[28:29], v[136:137]
	v_pk_mul_f32 v[24:25], v[24:25], v[140:141]
	v_pk_mul_f32 v[34:35], v[34:35], v[134:135]
	v_pk_mul_f32 v[30:31], v[30:31], v[138:139]
	v_pk_mul_f32 v[26:27], v[26:27], v[142:143]
	v_pk_mul_f32 v[22:23], v[22:23], v[146:147]
	v_pk_mul_f32 v[20:21], v[20:21], v[144:145]
	v_pk_mul_f32 v[16:17], v[16:17], v[132:133]
	v_pk_mul_f32 v[12:13], v[12:13], v[136:137]
	v_pk_mul_f32 v[8:9], v[8:9], v[140:141]
	v_pk_mul_f32 v[18:19], v[18:19], v[134:135]
	v_pk_mul_f32 v[14:15], v[14:15], v[138:139]
	v_pk_mul_f32 v[10:11], v[10:11], v[142:143]
	v_pk_mul_f32 v[6:7], v[6:7], v[146:147]
	v_pk_mul_f32 v[4:5], v[4:5], v[144:145]
; __device__ __forceinline__ void partialSM(f32x16& p0, f32x16& p1, float& m_reg, float& mn, float& alpha) {
;   constexpr float C = SCALE * 1.4426950408889634f;
;   float pmax = p0[0]; for (int r = 1; r < 16; ++r) pmax = fmaxf(pmax, p0[r]); for (int r = 0; r < 16; ++r) pmax = fmaxf(pmax, p1[r]);
;   { auto rr = __builtin_amdgcn_permlane32_swap(__float_as_uint(pmax), __float_as_uint(pmax), false, false);
;     pmax = fmaxf(__uint_as_float(rr[0]), __uint_as_float(rr[1])); }
;   if (__builtin_expect(__all(pmax - m_reg <= THR / SCALE), 1)) { mn = m_reg; alpha = 1.f; }
;   else { mn = fmaxf(m_reg, pmax); alpha = __builtin_amdgcn_exp2f((m_reg - mn) * C); m_reg = mn; }
;   float mnC = -mn * C;
;   for (int r = 0; r < 16; ++r) p0[r] = fmaf(p0[r], C, mnC); for (int r = 0; r < 16; ++r) p1[r] = fmaf(p1[r], C, mnC);
;   for (int r = 0; r < 16; ++r) p0[r] = __builtin_amdgcn_exp2f(p0[r]);
; }
; __device__ __forceinline__ void qkt(f32x16& p0, f32x16& p1, const u16* Ks, const bf16x8* qr, int r32, int hi) {
;   p0 = f32x16{}; p1 = f32x16{};
;   for (int d0 = 0; d0 < 8; ++d0) { int cb = (d0 * 16 + hi * 8) * 2;
;     bf16x8 b0 = *reinterpret_cast<const bf16x8*>((const char*)Ks + KSWZ(r32, cb));
;     bf16x8 b1 = *reinterpret_cast<const bf16x8*>((const char*)Ks + KSWZ(32 + r32, cb));
;     p0 = __builtin_amdgcn_mfma_f32_32x32x16_bf16(b0, qr[d0], p0, 0, 0, 0);
;     p1 = __builtin_amdgcn_mfma_f32_32x32x16_bf16(b1, qr[d0], p1, 0, 0, 0); }
; }
.Lstg_r1:
	v_cndmask_b32_e64 v2, v2, v166, s[6:7]
	v_mul_f32_e32 v140, 0xbe0293ee, v2
	v_fmamk_f32 v93, v93, 0x3e0293ee, v140
	v_exp_f32_e32 v221, v93
	v_fmamk_f32 v84, v84, 0x3e0293ee, v140
	v_fmamk_f32 v85, v85, 0x3e0293ee, v140
	v_fmamk_f32 v86, v86, 0x3e0293ee, v140
	v_fmamk_f32 v87, v87, 0x3e0293ee, v140
	v_fmamk_f32 v88, v88, 0x3e0293ee, v140
	v_fmamk_f32 v89, v89, 0x3e0293ee, v140
	v_fmamk_f32 v90, v90, 0x3e0293ee, v140
	v_fmamk_f32 v91, v91, 0x3e0293ee, v140
	v_fmamk_f32 v92, v92, 0x3e0293ee, v140
	v_fmamk_f32 v94, v94, 0x3e0293ee, v140
	v_fmamk_f32 v95, v95, 0x3e0293ee, v140
	v_fmamk_f32 v96, v96, 0x3e0293ee, v140
	v_fmamk_f32 v97, v97, 0x3e0293ee, v140
	v_fmamk_f32 v98, v98, 0x3e0293ee, v140
	v_fmamk_f32 v99, v99, 0x3e0293ee, v140
	v_fmamk_f32 v141, v68, 0x3e0293ee, v140
	v_fmamk_f32 v142, v69, 0x3e0293ee, v140
	v_fmamk_f32 v143, v70, 0x3e0293ee, v140
	v_fmamk_f32 v144, v71, 0x3e0293ee, v140
	v_fmamk_f32 v145, v72, 0x3e0293ee, v140
	v_fmamk_f32 v146, v73, 0x3e0293ee, v140
	v_fmamk_f32 v147, v74, 0x3e0293ee, v140
	v_fmamk_f32 v166, v75, 0x3e0293ee, v140
	v_fmamk_f32 v203, v76, 0x3e0293ee, v140
	v_fmamk_f32 v204, v77, 0x3e0293ee, v140
	v_fmamk_f32 v205, v78, 0x3e0293ee, v140
	v_fmamk_f32 v206, v79, 0x3e0293ee, v140
	v_fmamk_f32 v207, v80, 0x3e0293ee, v140
	v_fmamk_f32 v208, v81, 0x3e0293ee, v140
	v_fmamk_f32 v209, v82, 0x3e0293ee, v140
	v_fmac_f32_e32 v140, 0x3e0293ee, v83
	v_exp_f32_e32 v210, v84
	v_exp_f32_e32 v211, v85
	v_exp_f32_e32 v212, v86
	v_exp_f32_e32 v213, v87
	v_exp_f32_e32 v214, v88
	v_exp_f32_e32 v215, v89
	v_exp_f32_e32 v216, v90
	v_exp_f32_e32 v217, v91
	v_exp_f32_e32 v218, v92
	v_exp_f32_e32 v222, v94
	v_exp_f32_e32 v223, v95
	v_exp_f32_e32 v224, v96
	v_exp_f32_e32 v225, v97
	v_exp_f32_e32 v226, v98
	v_exp_f32_e32 v227, v99
	v_add_u32_e32 v254, s95, v189
	ds_read_b128 v[68:71], v254 offset:49152
	ds_read_b128 v[72:75], v254 offset:49280
	v_add_u32_e32 v254, s95, v190
	ds_read_b128 v[76:79], v254 offset:49152
	ds_read_b128 v[80:83], v254 offset:49280
	v_add_u32_e32 v254, s95, v191
	ds_read_b128 v[228:231], v254 offset:49152
	ds_read_b128 v[232:235], v254 offset:49280
	v_add_u32_e32 v254, s95, v192
	ds_read_b128 v[236:239], v254 offset:49152
	ds_read_b128 v[240:243], v254 offset:49280
	v_add_u32_e32 v254, s95, v189
	ds_read_b128 v[246:249], v254 offset:57344
	ds_read_b128 v[250:253], v254 offset:57472
	v_exp_f32_e32 v140, v140
	v_exp_f32_e32 v139, v166
	v_add_f32_e32 v166, 0, v210
	v_add_f32_e32 v166, v211, v166
	v_add_f32_e32 v166, v212, v166
	v_add_f32_e32 v166, v213, v166
	v_add_f32_e32 v166, v214, v166
	v_add_f32_e32 v166, v215, v166
	v_add_f32_e32 v166, v216, v166
	v_add_f32_e32 v166, v217, v166
	v_add_f32_e32 v166, v218, v166
	v_add_f32_e32 v166, v221, v166
	s_waitcnt lgkmcnt(9)
	v_mfma_f32_32x32x16_bf16 v[84:99], v[68:71], v[100:103], 0
	v_add_f32_e32 v166, v222, v166
	v_add_f32_e32 v166, v223, v166
	v_exp_f32_e32 v132, v141
	v_add_f32_e32 v166, v224, v166
	v_exp_f32_e32 v133, v142
	s_waitcnt lgkmcnt(8)
	v_mfma_f32_32x32x16_bf16 v[84:99], v[72:75], v[116:119], v[84:99]
	v_add_f32_e32 v166, v225, v166
	v_exp_f32_e32 v134, v143
	v_add_f32_e32 v166, v226, v166
	v_exp_f32_e32 v135, v144
	v_add_f32_e32 v166, v227, v166
	s_waitcnt lgkmcnt(7)
	v_mfma_f32_32x32x16_bf16 v[84:99], v[76:79], v[104:107], v[84:99]
	v_exp_f32_e32 v136, v145
	v_add_f32_e32 v166, v132, v166
	v_exp_f32_e32 v137, v146
	v_add_f32_e32 v166, v133, v166
	v_exp_f32_e32 v138, v147
	s_waitcnt lgkmcnt(6)
	v_mfma_f32_32x32x16_bf16 v[84:99], v[80:83], v[120:123], v[84:99]
	v_add_f32_e32 v166, v134, v166
	v_add_f32_e32 v166, v135, v166
	v_exp_f32_e32 v141, v203
	v_add_f32_e32 v166, v136, v166
	v_exp_f32_e32 v142, v204
	s_waitcnt lgkmcnt(5)
	v_mfma_f32_32x32x16_bf16 v[84:99], v[228:231], v[108:111], v[84:99]
	v_add_u32_e32 v254, s95, v190
	ds_read_b128 v[228:231], v254 offset:57344
	v_add_f32_e32 v166, v137, v166
	v_exp_f32_e32 v143, v205
	v_add_f32_e32 v166, v138, v166
	v_exp_f32_e32 v144, v206
	v_add_f32_e32 v166, v139, v166
	s_waitcnt lgkmcnt(5)
	v_mfma_f32_32x32x16_bf16 v[84:99], v[232:235], v[124:127], v[84:99]
	ds_read_b128 v[232:235], v254 offset:57472
	v_exp_f32_e32 v145, v207
	v_add_f32_e32 v166, v141, v166
	v_exp_f32_e32 v146, v208
	v_add_f32_e32 v166, v142, v166
	v_exp_f32_e32 v147, v209
	s_waitcnt lgkmcnt(5)
	v_mfma_f32_32x32x16_bf16 v[84:99], v[236:239], v[112:115], v[84:99]
	v_add_u32_e32 v254, s95, v191
	ds_read_b128 v[236:239], v254 offset:57344
	v_add_f32_e32 v166, v143, v166
	v_add_f32_e32 v166, v144, v166
	v_add_f32_e32 v166, v145, v166
	v_add_f32_e32 v166, v146, v166
	v_add_f32_e32 v166, v147, v166
	s_waitcnt lgkmcnt(5)
	v_mfma_f32_32x32x16_bf16 v[84:99], v[240:243], v[128:131], v[84:99]
	ds_read_b128 v[240:243], v254 offset:57472
	v_add_f32_e32 v219, v140, v166
	v_mov_b32_e32 v220, v219
	s_nop 1
	v_permlane32_swap_b32_e32 v219, v220
	s_waitcnt lgkmcnt(5)
	v_mfma_f32_32x32x16_bf16 v[68:83], v[246:249], v[100:103], 0
	v_add_u32_e32 v254, s95, v192
	ds_read_b128 v[246:249], v254 offset:57344
	v_cvt_pk_bf16_f32 v204, v210, v211
	v_cvt_pk_bf16_f32 v205, v212, v213
	v_cvt_pk_bf16_f32 v206, v214, v215
	v_cvt_pk_bf16_f32 v207, v216, v217
	s_waitcnt lgkmcnt(5)
	v_mfma_f32_32x32x16_bf16 v[68:83], v[250:253], v[116:119], v[68:83]
	ds_read_b128 v[250:253], v254 offset:57472
	v_cvt_pk_bf16_f32 v208, v218, v221
	v_cvt_pk_bf16_f32 v209, v222, v223
	v_cvt_pk_bf16_f32 v210, v224, v225
	v_cvt_pk_bf16_f32 v211, v226, v227
	s_waitcnt lgkmcnt(5)
	v_mfma_f32_32x32x16_bf16 v[68:83], v[228:231], v[104:107], v[68:83]
	v_cvt_pk_bf16_f32 v212, v132, v133
	v_cvt_pk_bf16_f32 v213, v134, v135
	v_cvt_pk_bf16_f32 v214, v136, v137
	v_cvt_pk_bf16_f32 v215, v138, v139
	s_waitcnt lgkmcnt(4)
; #define SBAR() __builtin_amdgcn_sched_barrier(0)
; #define QKT(P0, P1, KS) do { if (MODE == 1) qkt_lds(P0, P1, KS, qs, r32, hi); else qkt(P0, P1, KS, qr, r32, hi); } while (0)
; #define SWRITE(b, i) do { *(bf16x8*)((char*)V_lds + (b) * SHM_V + vst0) = sr_[i].vs0;          \
;     *(bf16x8*)((char*)V_lds + (b) * SHM_V + vst1) = sr_[i].vs1; int kc = sc * 2;               \
;     *(bf16x8*)((char*)K_lds + (b) * SHM_K + KSWZ(sr, kc)) = sr_[i].ks0;                       \
;     *(bf16x8*)((char*)K_lds + (b) * SHM_K + KSWZ(32 + sr, kc)) = sr_[i].ks1; } while (0)
; #define SWAIT() do { if (SD == 2) asm volatile("s_waitcnt vmcnt(4)" ::: "memory"); else asm volatile("s_waitcnt vmcnt(0)" ::: "memory"); } while (0)
; template <int D0> __device__ __forceinline__ void pv_one(f32x16& od, int vb, bf16x8 pa0, bf16x8 pa1, bf16x8 pa2, bf16x8 pa3) {
;   const s16x4 l0 = tr_read<v_rd_off(D0, 0, 0)>(vb), h0 = tr_read<v_rd_off(D0, 0, 1)>(vb), l1 = tr_read<v_rd_off(D0, 1, 0)>(vb), h1 = tr_read<v_rd_off(D0, 1, 1)>(vb);
;   const s16x4 l2 = tr_read<v_rd_off(D0, 2, 0)>(vb), h2 = tr_read<v_rd_off(D0, 2, 1)>(vb), l3 = tr_read<v_rd_off(D0, 3, 0)>(vb), h3 = tr_read<v_rd_off(D0, 3, 1)>(vb);
;   asm volatile("s_waitcnt lgkmcnt(0)" ::: "memory"); SBAR();
;     ...
;   od = __builtin_amdgcn_mfma_f32_32x32x16_bf16(pa0, PK(l0, h0), od, 0, 0, 0);
;   od = __builtin_amdgcn_mfma_f32_32x32x16_bf16(pa1, PK(l1, h1), od, 0, 0, 0);
;   od = __builtin_amdgcn_mfma_f32_32x32x16_bf16(pa2, PK(l2, h2), od, 0, 0, 0);
;   od = __builtin_amdgcn_mfma_f32_32x32x16_bf16(pa3, PK(l3, h3), od, 0, 0, 0);
;     ...
; }
; __device__ __forceinline__ void pv_d0(f32x16* o, int vb, bf16x8 pa0, bf16x8 pa1, bf16x8 pa2, bf16x8 pa3) {
;   pv_one<0>(o[0], vb, pa0, pa1, pa2, pa3); pv_one<1>(o[1], vb, pa0, pa1, pa2, pa3); pv_one<2>(o[2], vb, pa0, pa1, pa2, pa3); pv_one<3>(o[3], vb, pa0, pa1, pa2, pa3);
; template <int MODE> ...
;     ...
;       SBAR(); QKT(pB0, pB1, (u16*)((char*)K_lds + s0_ * SHM_K));
;       finishSM(pA0, pA1, alA, l_reg, pa0, pa1, pa2, pa3); SBAR();
;       { const int tn = (j + 2 < NT) ? j + 2 : NT - 1; SLOAD(SO, tn); } SBAR();
;       pv_d0(o, vb0 + s2_ * (int)SHM_V, pa0, pa1, pa2, pa3); partialSM(pB0, pB1, m_reg, mnB, alB);
;       SWAIT(); SWRITE(s1_, SE);
	v_mfma_f32_32x32x16_bf16 v[68:83], v[232:235], v[120:123], v[68:83]
	v_cvt_pk_bf16_f32 v222, v141, v142
	v_cvt_pk_bf16_f32 v223, v143, v144
	v_cvt_pk_bf16_f32 v224, v145, v146
	v_cvt_pk_bf16_f32 v225, v147, v140
	s_waitcnt lgkmcnt(3)
	v_mfma_f32_32x32x16_bf16 v[68:83], v[236:239], v[108:111], v[68:83]
	s_nop 0
	v_permlane32_swap_b32_e32 v204, v206
	v_permlane32_swap_b32_e32 v205, v207
	v_permlane32_swap_b32_e32 v208, v210
	s_waitcnt lgkmcnt(2)
	v_mfma_f32_32x32x16_bf16 v[68:83], v[240:243], v[124:127], v[68:83]
	v_permlane32_swap_b32_e32 v209, v211
	v_permlane32_swap_b32_e32 v212, v214
	v_permlane32_swap_b32_e32 v213, v215
	v_permlane32_swap_b32_e32 v222, v224
	s_waitcnt lgkmcnt(1)
	v_mfma_f32_32x32x16_bf16 v[68:83], v[246:249], v[112:115], v[68:83]
	v_permlane32_swap_b32_e32 v223, v225
	s_min_u32 s7, s16, s90
	s_add_i32 s7, s7, s88
	s_lshl_b32 s7, s7, 6
	s_waitcnt lgkmcnt(0)
	v_mfma_f32_32x32x16_bf16 v[68:83], v[250:253], v[128:131], v[68:83]
	v_add_u32_e32 v244, s7, v167
	v_add_u32_e32 v245, s7, v185
	v_lshl_or_b32 v244, v244, 8, v182
	v_lshl_or_b32 v245, v245, 8, v182
	global_load_dwordx4 v[136:139], v244, s[58:59]
	global_load_dwordx4 v[132:135], v245, s[58:59]
	global_load_dwordx4 v[144:147], v244, s[64:65]
	global_load_dwordx4 v[140:143], v245, s[64:65]
	v_add_u32_e32 v254, s93, v197
	ds_read_b64_tr_b16 v[230:231], v254 offset:0
	ds_read_b64_tr_b16 v[232:233], v254 offset:2048
	ds_read_b64_tr_b16 v[234:235], v254 offset:4096
	ds_read_b64_tr_b16 v[236:237], v254 offset:6144
	ds_read_b64_tr_b16 v[238:239], v254 offset:8192
	ds_read_b64_tr_b16 v[240:241], v254 offset:10240
	ds_read_b64_tr_b16 v[242:243], v254 offset:12288
	ds_read_b64_tr_b16 v[244:245], v254 offset:14336
	ds_read_b64_tr_b16 v[246:247], v254 offset:512
	ds_read_b64_tr_b16 v[248:249], v254 offset:2560
	s_waitcnt lgkmcnt(6)
	v_mfma_f32_32x32x16_bf16 v[52:67], v[204:207], v[230:233], v[52:67]
	ds_read_b64_tr_b16 v[250:251], v254 offset:4608
	ds_read_b64_tr_b16 v[252:253], v254 offset:6656
	v_mfma_f32_32x32x16_bf16 v[52:67], v[208:211], v[234:237], v[52:67]
	ds_read_b64_tr_b16 v[230:231], v254 offset:8704
	ds_read_b64_tr_b16 v[232:233], v254 offset:10752
	s_waitcnt lgkmcnt(6)
	v_mfma_f32_32x32x16_bf16 v[52:67], v[212:215], v[238:241], v[52:67]
	ds_read_b64_tr_b16 v[234:235], v254 offset:12800
	ds_read_b64_tr_b16 v[236:237], v254 offset:14848
	v_mfma_f32_32x32x16_bf16 v[52:67], v[222:225], v[242:245], v[52:67]
	ds_read_b64_tr_b16 v[238:239], v254 offset:1024
	ds_read_b64_tr_b16 v[240:241], v254 offset:3072
	s_waitcnt lgkmcnt(6)
	v_mfma_f32_32x32x16_bf16 v[36:51], v[204:207], v[246:249], v[36:51]
	ds_read_b64_tr_b16 v[242:243], v254 offset:5120
	ds_read_b64_tr_b16 v[244:245], v254 offset:7168
	v_mfma_f32_32x32x16_bf16 v[36:51], v[208:211], v[250:253], v[36:51]
	ds_read_b64_tr_b16 v[246:247], v254 offset:9216
	ds_read_b64_tr_b16 v[248:249], v254 offset:11264
	s_waitcnt lgkmcnt(6)
	v_mfma_f32_32x32x16_bf16 v[36:51], v[212:215], v[230:233], v[36:51]
	ds_read_b64_tr_b16 v[250:251], v254 offset:13312
	ds_read_b64_tr_b16 v[252:253], v254 offset:15360
	v_mfma_f32_32x32x16_bf16 v[36:51], v[222:225], v[234:237], v[36:51]
	ds_read_b64_tr_b16 v[230:231], v254 offset:1536
	ds_read_b64_tr_b16 v[232:233], v254 offset:3584
	s_waitcnt lgkmcnt(6)
	v_mfma_f32_32x32x16_bf16 v[20:35], v[204:207], v[238:241], v[20:35]
	ds_read_b64_tr_b16 v[234:235], v254 offset:5632
	ds_read_b64_tr_b16 v[236:237], v254 offset:7680
	v_mfma_f32_32x32x16_bf16 v[20:35], v[208:211], v[242:245], v[20:35]
	ds_read_b64_tr_b16 v[238:239], v254 offset:9728
	ds_read_b64_tr_b16 v[240:241], v254 offset:11776
	s_waitcnt lgkmcnt(6)
	v_mfma_f32_32x32x16_bf16 v[20:35], v[212:215], v[246:249], v[20:35]
	ds_read_b64_tr_b16 v[242:243], v254 offset:13824
	ds_read_b64_tr_b16 v[244:245], v254 offset:15872
	v_mfma_f32_32x32x16_bf16 v[20:35], v[222:225], v[250:253], v[20:35]
	s_waitcnt lgkmcnt(4)
	v_mfma_f32_32x32x16_bf16 v[4:19], v[204:207], v[230:233], v[4:19]
	v_mfma_f32_32x32x16_bf16 v[4:19], v[208:211], v[234:237], v[4:19]
	s_waitcnt lgkmcnt(0)
	v_mfma_f32_32x32x16_bf16 v[4:19], v[212:215], v[238:241], v[4:19]
	v_mfma_f32_32x32x16_bf16 v[4:19], v[222:225], v[242:245], v[4:19]
	s_add_i32 s30, s94, 0
	v_add_u32_e32 v203, s30, v184
	s_waitcnt vmcnt(4)
	ds_write_b128 v203, v[152:155]
	v_add_u32_e32 v152, s30, v186
	ds_write_b128 v152, v[148:151]
	v_add_u32_e32 v148, s30, v187
	ds_write_b128 v148, v[160:163] offset:49152
	v_add_u32_e32 v148, s30, v188
	s_waitcnt vmcnt(4)
	ds_write_b128 v148, v[156:159] offset:49152
	s_waitcnt lgkmcnt(0)
	s_barrier
; __device__ __forceinline__ void partialSM(f32x16& p0, f32x16& p1, float& m_reg, float& mn, float& alpha) {
;   constexpr float C = SCALE * 1.4426950408889634f;
;   float pmax = p0[0]; for (int r = 1; r < 16; ++r) pmax = fmaxf(pmax, p0[r]); for (int r = 0; r < 16; ++r) pmax = fmaxf(pmax, p1[r]);
;   { auto rr = __builtin_amdgcn_permlane32_swap(__float_as_uint(pmax), __float_as_uint(pmax), false, false);
;     pmax = fmaxf(__uint_as_float(rr[0]), __uint_as_float(rr[1])); }
;   if (__builtin_expect(__all(pmax - m_reg <= THR / SCALE), 1)) { mn = m_reg; alpha = 1.f; }
;   else { mn = fmaxf(m_reg, pmax); alpha = __builtin_amdgcn_exp2f((m_reg - mn) * C); m_reg = mn; }
	v_max_f32_e32 v166, v85, v85
	v_max_f32_e32 v203, v84, v84
	v_max_f32_e32 v166, v203, v166
	v_max3_f32 v166, v166, v86, v87
	v_max3_f32 v166, v166, v88, v89
	v_max3_f32 v166, v166, v90, v91
	v_max3_f32 v166, v166, v92, v93
	v_max3_f32 v166, v166, v94, v95
	v_max3_f32 v166, v166, v96, v97
	v_max3_f32 v166, v166, v98, v99
	v_max3_f32 v166, v166, v68, v69
	v_max3_f32 v166, v166, v70, v71
	v_max3_f32 v166, v166, v72, v73
	v_max3_f32 v166, v166, v74, v75
	v_max3_f32 v166, v166, v76, v77
	v_max3_f32 v166, v166, v78, v79
	v_max3_f32 v166, v166, v80, v81
	v_max3_f32 v166, v166, v82, v83
	v_mov_b32_e32 v203, v166
	s_nop 1
	v_permlane32_swap_b32_e32 v166, v203
	v_max_f32_e32 v203, v203, v203
	v_max_f32_e32 v166, v166, v166
	v_max_f32_e32 v166, v166, v203
	v_sub_f32_e32 v203, v166, v2
	v_cmp_ge_f32_e32 vcc, s74, v203
	v_max_f32_e32 v203, v2, v2
	v_max_f32_e32 v166, v203, v166
	v_sub_f32_e32 v203, v2, v166
	v_mul_f32_e32 v203, 0x3e0293ee, v203
	v_exp_f32_e32 v203, v203
	s_cmp_eq_u64 vcc, exec
	s_cselect_b64 s[6:7], -1, 0
	v_cndmask_b32_e64 v221, v203, 1.0, s[6:7]
	v_cmp_gt_f32_e32 vcc, 1.0, v221
	s_cbranch_vccz .Lstg_r2
	s_and_saveexec_b64 s[66:67], s[4:5]
	ds_write_b32 v183, v221 offset:128
	s_or_b64 exec, exec, s[66:67]
	s_waitcnt lgkmcnt(0)
	v_add_u32_e32 v160, v181, v180
	ds_read_b128 v[148:151], v160 offset:224
	ds_read_b128 v[152:155], v160 offset:192
	ds_read_b128 v[156:159], v160 offset:160
	ds_read_b128 v[160:163], v160 offset:128
	s_waitcnt lgkmcnt(3)
	v_pk_mul_f32 v[64:65], v[64:65], v[148:149]
	s_waitcnt lgkmcnt(2)
	v_pk_mul_f32 v[60:61], v[60:61], v[152:153]
	s_waitcnt lgkmcnt(1)
	v_pk_mul_f32 v[56:57], v[56:57], v[156:157]
	v_pk_mul_f32 v[66:67], v[66:67], v[150:151]
	v_pk_mul_f32 v[62:63], v[62:63], v[154:155]
	v_pk_mul_f32 v[58:59], v[58:59], v[158:159]
	s_waitcnt lgkmcnt(0)
	v_pk_mul_f32 v[54:55], v[54:55], v[162:163]
	v_pk_mul_f32 v[52:53], v[52:53], v[160:161]
	v_pk_mul_f32 v[48:49], v[48:49], v[148:149]
	v_pk_mul_f32 v[44:45], v[44:45], v[152:153]
	v_pk_mul_f32 v[40:41], v[40:41], v[156:157]
	v_pk_mul_f32 v[50:51], v[50:51], v[150:151]
	v_pk_mul_f32 v[46:47], v[46:47], v[154:155]
	v_pk_mul_f32 v[42:43], v[42:43], v[158:159]
	v_pk_mul_f32 v[38:39], v[38:39], v[162:163]
	v_pk_mul_f32 v[36:37], v[36:37], v[160:161]
	v_pk_mul_f32 v[32:33], v[32:33], v[148:149]
	v_pk_mul_f32 v[28:29], v[28:29], v[152:153]
	v_pk_mul_f32 v[24:25], v[24:25], v[156:157]
	v_pk_mul_f32 v[34:35], v[34:35], v[150:151]
	v_pk_mul_f32 v[30:31], v[30:31], v[154:155]
	v_pk_mul_f32 v[26:27], v[26:27], v[158:159]
	v_pk_mul_f32 v[22:23], v[22:23], v[162:163]
	v_pk_mul_f32 v[20:21], v[20:21], v[160:161]
	v_pk_mul_f32 v[16:17], v[16:17], v[148:149]
	v_pk_mul_f32 v[12:13], v[12:13], v[152:153]
	v_pk_mul_f32 v[8:9], v[8:9], v[156:157]
	v_pk_mul_f32 v[18:19], v[18:19], v[150:151]
	v_pk_mul_f32 v[14:15], v[14:15], v[154:155]
	v_pk_mul_f32 v[10:11], v[10:11], v[158:159]
	v_pk_mul_f32 v[6:7], v[6:7], v[162:163]
	v_pk_mul_f32 v[4:5], v[4:5], v[160:161]
